# EpiUp neighbour fetches via DPP row_ror instead of ds_bpermute; SB next-tile address math via scalar base + 32-bit offsets
# speedup vs baseline: 1.0270x; 1.0096x over previous
; #define LAS __attribute__((address_space(3)))
; __device__ NOINL void sb_unit(unsigned char* ws, LAS unsigned char* lds, int unit, int wv) {
;     ...
;     SB_ISSUE((t0 + 14) >> 5);
;     ...
;         const int s0 = tile * 32;
; #pragma unroll
;         for (int i = 0; i < 8; ++i) *(LAS u32x4*)(vb + ((lane >> 4) + 4 * i) * 256 + (lane & 15) * 16) = vpf[i];
;         bf16x8 kcur[2][4];
; #pragma unroll
;         for (int a = 0; a < 2; ++a)
; #pragma unroll
;             for (int ks = 0; ks < 4; ++ks) kcur[a][ks] = kpf[a][ks];
;         if (tile > 0) SB_ISSUE(tile - 1);
.LBB0_362:
	v_subrev_co_u32_e32 v164, vcc, 1, v163
	s_and_b64 vcc, exec, vcc
	ds_write_b128 v161, v[58:61]
	ds_write_b128 v161, v[50:53] offset:1024
	ds_write_b128 v161, v[66:69] offset:2048
	ds_write_b128 v161, v[54:57] offset:3072
	ds_write_b128 v161, v[74:77] offset:4096
	ds_write_b128 v161, v[62:65] offset:5120
	ds_write_b128 v161, v[78:81] offset:6144
	ds_write_b128 v161, v[70:73] offset:7168
	s_cbranch_vccnz .LBB0_364
	s_add_u32 s36, s24, s26
	s_addc_u32 s37, s25, 0
	s_add_u32 s46, s36, 0x1800
	s_addc_u32 s47, s37, 0
	s_add_u32 s36, s36, 0x1000
	s_addc_u32 s37, s37, 0
	v_add_u32_e32 v192, s70, v146
	v_lshl_add_u32 v192, v192, 14, v150
	v_add_u32_e32 v193, 0x10000, v192
	v_add_u32_e32 v194, 0x20000, v192
	v_add_u32_e32 v195, 0x30000, v192
	v_add_u32_e32 v196, 0x40000, v192
	v_add_u32_e32 v197, 0x50000, v192
	v_add_u32_e32 v198, 0x60000, v192
	v_add_u32_e32 v199, 0x70000, v192
	v_add_u32_e32 v200, s70, v148
	v_lshl_add_u32 v200, v200, 14, v152
	v_add_u32_e32 v201, 0x40000, v200
	global_load_dwordx4 v[58:61], v192, s[46:47]
	global_load_dwordx4 v[50:53], v193, s[46:47]
	global_load_dwordx4 v[66:69], v194, s[46:47]
	global_load_dwordx4 v[54:57], v195, s[46:47]
	global_load_dwordx4 v[74:77], v196, s[46:47]
	global_load_dwordx4 v[62:65], v197, s[46:47]
	global_load_dwordx4 v[78:81], v198, s[46:47]
	global_load_dwordx4 v[70:73], v199, s[46:47]
	global_load_dwordx4 v[82:85], v200, s[36:37] offset:64
	global_load_dwordx4 v[90:93], v200, s[36:37] offset:128
	global_load_dwordx4 v[86:89], v200, s[36:37]
	global_load_dwordx4 v[94:97], v200, s[36:37] offset:192
	global_load_dwordx4 v[98:101], v201, s[36:37] offset:64
	global_load_dwordx4 v[106:109], v201, s[36:37] offset:128
	global_load_dwordx4 v[102:105], v201, s[36:37]
	global_load_dwordx4 v[110:113], v201, s[36:37] offset:192

; #define PG8_STAGE(bufoff, gbase, voff) do { _Pragma("unroll") for (int _i = 0; _i < 2; ++_i) \
;         __builtin_amdgcn_global_load_lds((const unsigned*)((const char*)(gbase) + (voff)[_i]), (LAS unsigned*)(lds + (bufoff) + ldsw + _i * 8192), 16, 0, 0); } while (0)
; #define PG8_LDA(dst, b, h) do { _Pragma("unroll") for (int m = 0; m < 4; ++m) _Pragma("unroll") for (int k = 0; k < 2; ++k) dst[m][k] = *(const LAS bf16x8*)(lds + PG8_SA(b, h) + aoff + m * 2048 + k * 1024); } while (0)
; #define PG8_LDB(dst, b, h) do { _Pragma("unroll") for (int n = 0; n < 2; ++n) _Pragma("unroll") for (int k = 0; k < 2; ++k) dst[n][k] = *(const LAS bf16x8*)(lds + PG8_SB(b, h) + boff + n * 2048 + k * 1024); } while (0)
; #define PG8_MMA(ai, bj, At, Bt) do { __builtin_amdgcn_s_setprio(1); _Pragma("unroll") for (int m = 0; m < 4; ++m) _Pragma("unroll") for (int n = 0; n < 2; ++n) _Pragma("unroll") for (int k = 0; k < 2; ++k) \
;         acc[ai][bj][m][n] = __builtin_amdgcn_mfma_f32_16x16x32_bf16(Bt[n][k], At[m][k], acc[ai][bj][m][n], 0, 0, 0); __builtin_amdgcn_s_setprio(0); } while (0)
; #define PG8_WAIT_L(n) asm volatile("s_waitcnt lgkmcnt(" #n ")" ::: "memory")
; #define PG8_BAR __builtin_amdgcn_s_barrier()
; #define PG8_SCHED __builtin_amdgcn_sched_barrier(0)
; template <class Epi, class Sched, bool AREMAP>
; __device__ __forceinline__ void gemm_phase(LAS unsigned char* lds, const Gemm g, const Sched& S, const Epi& E, int wv) {
;     ...
;             const char* a1 = cA + (size_t)(t + 1) * kstep;
;             const char* a2 = last ? nA : cA + (size_t)(t + 2) * kstep; const char* b2 = last ? nB : cB + (size_t)(t + 2) * kstep;
;             const char* a3 = a2 + kstep; const char* b3 = b2 + kstep;
;             PG8_LDB(B0, 0, 0); PG8_SCHED; PG8_LDA(At, 0, 0); PG8_STAGE(PG8_SA(1, 1), a1 + hstepA, voffA);
;             PG8_WAIT_L(8); PG8_BAR; PG8_WAIT_L(0); PG8_MMA(0, 0, At, B0); PG8_BAR; PG8_SCHED;
;             PG8_LDB(B1, 0, 1); PG8_STAGE(PG8_SB(0, 0), b2, voffB);
;             PG8_BAR; PG8_WAIT_L(0); PG8_MMA(0, 1, At, B1); PG8_BAR;
;             PG8_LDA(At, 0, 1); PG8_STAGE(PG8_SA(0, 0), a2, voffA);
;             PG8_BAR; PG8_WAIT_L(0); PG8_MMA(1, 0, At, B0); PG8_BAR; PG8_SCHED;
.LBB0_619:
	s_add_u32 s38, s78, 0xfffc0080
	s_addc_u32 s39, s79, -1
	s_add_i32 s33, 0, 0x10000
	v_add_u32_e32 v142, s33, v1
	ds_read_b128 v[130:133], v142
	ds_read_b128 v[134:137], v142 offset:1024
	ds_read_b128 v[138:141], v142 offset:2048
	ds_read_b128 v[142:145], v142 offset:3072
	s_cmp_eq_u32 vcc_hi, 28
	s_cselect_b32 s97, s46, s39
	s_cselect_b32 s96, s47, s38
	s_cselect_b32 s81, s63, vcc_lo
	s_cselect_b32 s80, s67, s77
	v_lshl_add_u64 v[178:179], s[78:79], 0, v[168:169]
	s_add_i32 m0, s10, 0xc000
	ds_read_b128 v[146:149], v183
	ds_read_b128 v[150:153], v183 offset:1024
	ds_read_b128 v[170:173], v183 offset:2048
	ds_read_b128 v[174:177], v183 offset:3072
	ds_read_b128 v[184:187], v183 offset:4096
	ds_read_b128 v[192:195], v183 offset:5120
	ds_read_b128 v[196:199], v183 offset:6144
	ds_read_b128 v[200:203], v183 offset:7168
	global_load_lds_dwordx4 v[178:179], off
	v_lshl_add_u64 v[178:179], s[78:79], 0, v[166:167]
	s_add_i32 m0, s10, 0xe000
	s_nop 0
	global_load_lds_dwordx4 v[178:179], off
	s_waitcnt lgkmcnt(8)
	s_barrier
	s_waitcnt lgkmcnt(0)
	s_setprio 1
	s_waitcnt lgkmcnt(0)
	v_mfma_f32_16x16x32_bf16 v[126:129], v[130:133], v[146:149], v[126:129]
	v_mfma_f32_16x16x32_bf16 v[62:65], v[138:141], v[146:149], v[62:65]
	v_mfma_f32_16x16x32_bf16 v[118:121], v[130:133], v[170:173], v[118:121]
	v_mfma_f32_16x16x32_bf16 v[54:57], v[138:141], v[170:173], v[54:57]
	v_mfma_f32_16x16x32_bf16 v[110:113], v[130:133], v[184:187], v[110:113]
	v_mfma_f32_16x16x32_bf16 v[46:49], v[138:141], v[184:187], v[46:49]
	v_mfma_f32_16x16x32_bf16 v[102:105], v[130:133], v[196:199], v[102:105]
	v_mfma_f32_16x16x32_bf16 v[38:41], v[138:141], v[196:199], v[38:41]
	v_mfma_f32_16x16x32_bf16 v[126:129], v[134:137], v[150:153], v[126:129]
	v_mfma_f32_16x16x32_bf16 v[62:65], v[142:145], v[150:153], v[62:65]
	v_mfma_f32_16x16x32_bf16 v[118:121], v[134:137], v[174:177], v[118:121]
	v_mfma_f32_16x16x32_bf16 v[54:57], v[142:145], v[174:177], v[54:57]
	v_mfma_f32_16x16x32_bf16 v[110:113], v[134:137], v[192:195], v[110:113]
	v_mfma_f32_16x16x32_bf16 v[46:49], v[142:145], v[192:195], v[46:49]
	v_mfma_f32_16x16x32_bf16 v[102:105], v[134:137], v[200:203], v[102:105]
	v_mfma_f32_16x16x32_bf16 v[38:41], v[142:145], v[200:203], v[38:41]
	s_setprio 0
	s_barrier
	s_add_i32 s58, 0, 0x14000
	v_add_u32_e32 v178, s58, v1
	s_add_i32 s33, s33, s91
	ds_read_b128 v[204:207], v178
	ds_read_b128 v[208:211], v178 offset:1024
	ds_read_b128 v[212:215], v178 offset:2048
	ds_read_b128 v[216:219], v178 offset:3072
	v_lshl_add_u64 v[178:179], s[80:81], 0, v[158:159]
	s_mov_b32 m0, s33
	v_lshl_add_u64 v[220:221], s[80:81], 0, v[154:155]
	global_load_lds_dwordx4 v[178:179], off
	s_add_i32 m0, s33, 0x2000
	s_nop 0
	global_load_lds_dwordx4 v[220:221], off
	s_barrier
	s_waitcnt lgkmcnt(0)
	s_setprio 1
	s_waitcnt lgkmcnt(0)
	v_mfma_f32_16x16x32_bf16 v[122:125], v[204:207], v[146:149], v[122:125]
	v_mfma_f32_16x16x32_bf16 v[58:61], v[212:215], v[146:149], v[58:61]
	v_mfma_f32_16x16x32_bf16 v[114:117], v[204:207], v[170:173], v[114:117]
	v_mfma_f32_16x16x32_bf16 v[50:53], v[212:215], v[170:173], v[50:53]
	v_mfma_f32_16x16x32_bf16 v[106:109], v[204:207], v[184:187], v[106:109]
	v_mfma_f32_16x16x32_bf16 v[42:45], v[212:215], v[184:187], v[42:45]
	v_mfma_f32_16x16x32_bf16 v[98:101], v[204:207], v[196:199], v[98:101]
	v_mfma_f32_16x16x32_bf16 v[34:37], v[212:215], v[196:199], v[34:37]
	v_mfma_f32_16x16x32_bf16 v[122:125], v[208:211], v[150:153], v[122:125]
	v_mfma_f32_16x16x32_bf16 v[58:61], v[216:219], v[150:153], v[58:61]
	v_mfma_f32_16x16x32_bf16 v[114:117], v[208:211], v[174:177], v[114:117]
	v_mfma_f32_16x16x32_bf16 v[50:53], v[216:219], v[174:177], v[50:53]
	v_mfma_f32_16x16x32_bf16 v[106:109], v[208:211], v[192:195], v[106:109]
	v_mfma_f32_16x16x32_bf16 v[42:45], v[216:219], v[192:195], v[42:45]
	v_mfma_f32_16x16x32_bf16 v[98:101], v[208:211], v[200:203], v[98:101]
	v_mfma_f32_16x16x32_bf16 v[34:37], v[216:219], v[200:203], v[34:37]
	s_setprio 0
	s_mov_b32 m0, s10
	v_lshl_add_u64 v[222:223], s[96:97], 0, v[160:161]
	s_barrier
	ds_read_b128 v[146:149], v183 offset:16384
	ds_read_b128 v[150:153], v183 offset:17408
	ds_read_b128 v[170:173], v183 offset:18432
	ds_read_b128 v[174:177], v183 offset:19456
	ds_read_b128 v[184:187], v183 offset:20480
	ds_read_b128 v[192:195], v183 offset:21504
	ds_read_b128 v[196:199], v183 offset:22528
	ds_read_b128 v[200:203], v183 offset:23552
	global_load_lds_dwordx4 v[222:223], off
	v_lshl_add_u64 v[224:225], s[96:97], 0, v[156:157]
	s_mov_b32 m0, s11
	s_nop 0
	global_load_lds_dwordx4 v[224:225], off
	s_barrier
	s_waitcnt lgkmcnt(0)
	s_setprio 1
	s_waitcnt lgkmcnt(0)
	v_mfma_f32_16x16x32_bf16 v[94:97], v[130:133], v[146:149], v[94:97]
	v_mfma_f32_16x16x32_bf16 v[30:33], v[138:141], v[146:149], v[30:33]
	v_mfma_f32_16x16x32_bf16 v[86:89], v[130:133], v[170:173], v[86:89]
	v_mfma_f32_16x16x32_bf16 v[22:25], v[138:141], v[170:173], v[22:25]
	v_mfma_f32_16x16x32_bf16 v[78:81], v[130:133], v[184:187], v[78:81]
	v_mfma_f32_16x16x32_bf16 v[14:17], v[138:141], v[184:187], v[14:17]
	v_mfma_f32_16x16x32_bf16 v[70:73], v[130:133], v[196:199], v[70:73]
	v_mfma_f32_16x16x32_bf16 v[6:9], v[138:141], v[196:199], v[6:9]
	v_mfma_f32_16x16x32_bf16 v[94:97], v[134:137], v[150:153], v[94:97]
	v_mfma_f32_16x16x32_bf16 v[30:33], v[142:145], v[150:153], v[30:33]
	v_mfma_f32_16x16x32_bf16 v[86:89], v[134:137], v[174:177], v[86:89]
	v_mfma_f32_16x16x32_bf16 v[22:25], v[142:145], v[174:177], v[22:25]
	v_mfma_f32_16x16x32_bf16 v[78:81], v[134:137], v[192:195], v[78:81]
	v_mfma_f32_16x16x32_bf16 v[14:17], v[142:145], v[192:195], v[14:17]
	v_mfma_f32_16x16x32_bf16 v[70:73], v[134:137], v[200:203], v[70:73]
	v_mfma_f32_16x16x32_bf16 v[6:9], v[142:145], v[200:203], v[6:9]
	s_setprio 0
	s_barrier
; #define PG8_STAGE(bufoff, gbase, voff) do { _Pragma("unroll") for (int _i = 0; _i < 2; ++_i) \
;         __builtin_amdgcn_global_load_lds((const unsigned*)((const char*)(gbase) + (voff)[_i]), (LAS unsigned*)(lds + (bufoff) + ldsw + _i * 8192), 16, 0, 0); } while (0)
; #define PG8_LDA(dst, b, h) do { _Pragma("unroll") for (int m = 0; m < 4; ++m) _Pragma("unroll") for (int k = 0; k < 2; ++k) dst[m][k] = *(const LAS bf16x8*)(lds + PG8_SA(b, h) + aoff + m * 2048 + k * 1024); } while (0)
; #define PG8_LDB(dst, b, h) do { _Pragma("unroll") for (int n = 0; n < 2; ++n) _Pragma("unroll") for (int k = 0; k < 2; ++k) dst[n][k] = *(const LAS bf16x8*)(lds + PG8_SB(b, h) + boff + n * 2048 + k * 1024); } while (0)
; #define PG8_MMA(ai, bj, At, Bt) do { __builtin_amdgcn_s_setprio(1); _Pragma("unroll") for (int m = 0; m < 4; ++m) _Pragma("unroll") for (int n = 0; n < 2; ++n) _Pragma("unroll") for (int k = 0; k < 2; ++k) \
;         acc[ai][bj][m][n] = __builtin_amdgcn_mfma_f32_16x16x32_bf16(Bt[n][k], At[m][k], acc[ai][bj][m][n], 0, 0, 0); __builtin_amdgcn_s_setprio(0); } while (0)
; #define PG8_WAIT_V(n) asm volatile("s_waitcnt vmcnt(" #n ")" ::: "memory")
; #define PG8_WAIT_L(n) asm volatile("s_waitcnt lgkmcnt(" #n ")" ::: "memory")
; #define PG8_BAR __builtin_amdgcn_s_barrier()
; #define PG8_SCHED __builtin_amdgcn_sched_barrier(0)
; template <class Epi, class Sched, bool AREMAP>
; __device__ __forceinline__ void gemm_phase(LAS unsigned char* lds, const Gemm g, const Sched& S, const Epi& E, int wv) {
;     ...
;             PG8_STAGE(PG8_SB(0, 1), b2 + hstepB, voffB);
;             PG8_WAIT_V(6); PG8_BAR; PG8_MMA(1, 1, At, B1); PG8_BAR;
;             PG8_LDB(B0, 1, 0); PG8_SCHED; PG8_LDA(At, 1, 0); PG8_STAGE(PG8_SA(0, 1), a2 + hstepA, voffA);
;             PG8_WAIT_L(8); PG8_BAR; PG8_WAIT_L(0); PG8_MMA(0, 0, At, B0); PG8_BAR; PG8_SCHED;
;             PG8_LDB(B1, 1, 1); PG8_STAGE(PG8_SB(1, 0), b3, voffB);
;             PG8_BAR; PG8_WAIT_L(0); PG8_MMA(0, 1, At, B1); PG8_BAR;
	s_add_u32 s38, s80, 0x80000
	s_addc_u32 s39, s81, 0
	s_add_i32 s33, s58, s91
	v_lshl_add_u64 v[130:131], s[38:39], 0, v[158:159]
	s_mov_b32 m0, s33
	s_nop 0
	global_load_lds_dwordx4 v[130:131], off
	v_lshl_add_u64 v[130:131], s[38:39], 0, v[154:155]
	s_add_i32 m0, s33, 0x2000
	s_nop 0
	global_load_lds_dwordx4 v[130:131], off
	s_waitcnt vmcnt(6)
	s_barrier
	s_setprio 1
	v_mfma_f32_16x16x32_bf16 v[90:93], v[204:207], v[146:149], v[90:93]
	v_mfma_f32_16x16x32_bf16 v[26:29], v[212:215], v[146:149], v[26:29]
	v_mfma_f32_16x16x32_bf16 v[82:85], v[204:207], v[170:173], v[82:85]
	v_mfma_f32_16x16x32_bf16 v[18:21], v[212:215], v[170:173], v[18:21]
	v_mfma_f32_16x16x32_bf16 v[74:77], v[204:207], v[184:187], v[74:77]
	v_mfma_f32_16x16x32_bf16 v[10:13], v[212:215], v[184:187], v[10:13]
	v_mfma_f32_16x16x32_bf16 v[66:69], v[204:207], v[196:199], v[66:69]
	v_mfma_f32_16x16x32_bf16 v[2:5], v[212:215], v[196:199], v[2:5]
	v_mfma_f32_16x16x32_bf16 v[90:93], v[208:211], v[150:153], v[90:93]
	v_mfma_f32_16x16x32_bf16 v[26:29], v[216:219], v[150:153], v[26:29]
	v_mfma_f32_16x16x32_bf16 v[82:85], v[208:211], v[174:177], v[82:85]
	v_mfma_f32_16x16x32_bf16 v[18:21], v[216:219], v[174:177], v[18:21]
	v_mfma_f32_16x16x32_bf16 v[74:77], v[208:211], v[192:195], v[74:77]
	v_mfma_f32_16x16x32_bf16 v[10:13], v[216:219], v[192:195], v[10:13]
	v_mfma_f32_16x16x32_bf16 v[66:69], v[208:211], v[200:203], v[66:69]
	v_mfma_f32_16x16x32_bf16 v[2:5], v[216:219], v[200:203], v[2:5]
	s_setprio 0
	s_add_i32 s33, 0, 0x18000
	v_add_u32_e32 v142, s33, v1
	s_barrier
	ds_read_b128 v[130:133], v142
	ds_read_b128 v[134:137], v142 offset:1024
	ds_read_b128 v[138:141], v142 offset:2048
	ds_read_b128 v[142:145], v142 offset:3072
	s_add_u32 s38, s96, 0x40000
	s_addc_u32 s39, s97, 0
	s_mov_b32 m0, s12
	v_lshl_add_u64 v[204:205], s[38:39], 0, v[160:161]
	ds_read_b128 v[146:149], v183 offset:32768
	ds_read_b128 v[150:153], v183 offset:33792
	ds_read_b128 v[170:173], v183 offset:34816
	ds_read_b128 v[174:177], v183 offset:35840
	ds_read_b128 v[184:187], v183 offset:36864
	ds_read_b128 v[192:195], v183 offset:37888
	ds_read_b128 v[196:199], v183 offset:38912
	ds_read_b128 v[200:203], v183 offset:39936
	global_load_lds_dwordx4 v[204:205], off
	v_lshl_add_u64 v[204:205], s[38:39], 0, v[156:157]
	s_mov_b32 m0, s13
	s_nop 0
	global_load_lds_dwordx4 v[204:205], off
	s_waitcnt lgkmcnt(8)
	s_barrier
	s_waitcnt lgkmcnt(0)
	s_setprio 1
	s_waitcnt lgkmcnt(0)
	v_mfma_f32_16x16x32_bf16 v[126:129], v[130:133], v[146:149], v[126:129]
	v_mfma_f32_16x16x32_bf16 v[62:65], v[138:141], v[146:149], v[62:65]
	v_mfma_f32_16x16x32_bf16 v[118:121], v[130:133], v[170:173], v[118:121]
	v_mfma_f32_16x16x32_bf16 v[54:57], v[138:141], v[170:173], v[54:57]
	v_mfma_f32_16x16x32_bf16 v[110:113], v[130:133], v[184:187], v[110:113]
	v_mfma_f32_16x16x32_bf16 v[46:49], v[138:141], v[184:187], v[46:49]
	v_mfma_f32_16x16x32_bf16 v[102:105], v[130:133], v[196:199], v[102:105]
	v_mfma_f32_16x16x32_bf16 v[38:41], v[138:141], v[196:199], v[38:41]
	v_mfma_f32_16x16x32_bf16 v[126:129], v[134:137], v[150:153], v[126:129]
	v_mfma_f32_16x16x32_bf16 v[62:65], v[142:145], v[150:153], v[62:65]
	v_mfma_f32_16x16x32_bf16 v[118:121], v[134:137], v[174:177], v[118:121]
	v_mfma_f32_16x16x32_bf16 v[54:57], v[142:145], v[174:177], v[54:57]
	v_mfma_f32_16x16x32_bf16 v[110:113], v[134:137], v[192:195], v[110:113]
	v_mfma_f32_16x16x32_bf16 v[46:49], v[142:145], v[192:195], v[46:49]
	v_mfma_f32_16x16x32_bf16 v[102:105], v[134:137], v[200:203], v[102:105]
	v_mfma_f32_16x16x32_bf16 v[38:41], v[142:145], v[200:203], v[38:41]
	s_setprio 0
	s_barrier
	s_add_i32 s58, 0, 0x1c000
	s_add_i32 s33, s33, s91
	v_add_u32_e32 v216, s58, v1
	v_lshl_add_u64 v[178:179], v[178:179], 0, s[86:87]
	s_mov_b32 m0, s33
	ds_read_b128 v[204:207], v216
	ds_read_b128 v[208:211], v216 offset:1024
	ds_read_b128 v[212:215], v216 offset:2048
	ds_read_b128 v[216:219], v216 offset:3072
	global_load_lds_dwordx4 v[178:179], off
	v_lshl_add_u64 v[178:179], v[220:221], 0, s[86:87]
	s_add_i32 m0, s33, 0x2000
	s_nop 0
	global_load_lds_dwordx4 v[178:179], off
	s_barrier
	s_waitcnt lgkmcnt(0)
	s_setprio 1
	s_waitcnt lgkmcnt(0)
	v_mfma_f32_16x16x32_bf16 v[122:125], v[204:207], v[146:149], v[122:125]
	v_mfma_f32_16x16x32_bf16 v[58:61], v[212:215], v[146:149], v[58:61]
	v_mfma_f32_16x16x32_bf16 v[114:117], v[204:207], v[170:173], v[114:117]
	v_mfma_f32_16x16x32_bf16 v[50:53], v[212:215], v[170:173], v[50:53]
	v_mfma_f32_16x16x32_bf16 v[106:109], v[204:207], v[184:187], v[106:109]
	v_mfma_f32_16x16x32_bf16 v[42:45], v[212:215], v[184:187], v[42:45]
	v_mfma_f32_16x16x32_bf16 v[98:101], v[204:207], v[196:199], v[98:101]
	v_mfma_f32_16x16x32_bf16 v[34:37], v[212:215], v[196:199], v[34:37]
	v_mfma_f32_16x16x32_bf16 v[122:125], v[208:211], v[150:153], v[122:125]
	v_mfma_f32_16x16x32_bf16 v[58:61], v[216:219], v[150:153], v[58:61]
	v_mfma_f32_16x16x32_bf16 v[114:117], v[208:211], v[174:177], v[114:117]
	v_mfma_f32_16x16x32_bf16 v[50:53], v[216:219], v[174:177], v[50:53]
	v_mfma_f32_16x16x32_bf16 v[106:109], v[208:211], v[192:195], v[106:109]
	v_mfma_f32_16x16x32_bf16 v[42:45], v[216:219], v[192:195], v[42:45]
	v_mfma_f32_16x16x32_bf16 v[98:101], v[208:211], v[200:203], v[98:101]
	v_mfma_f32_16x16x32_bf16 v[34:37], v[216:219], v[200:203], v[34:37]
	s_setprio 0
	s_mov_b32 m0, s14
	v_lshl_add_u64 v[178:179], v[222:223], 0, s[86:87]
	s_barrier
	ds_read_b128 v[146:149], v183 offset:49152
	ds_read_b128 v[150:153], v183 offset:50176
	ds_read_b128 v[170:173], v183 offset:51200
	ds_read_b128 v[174:177], v183 offset:52224
	ds_read_b128 v[184:187], v183 offset:53248
	ds_read_b128 v[192:195], v183 offset:54272
	ds_read_b128 v[196:199], v183 offset:55296
	ds_read_b128 v[200:203], v183 offset:56320
	global_load_lds_dwordx4 v[178:179], off
	v_lshl_add_u64 v[178:179], v[224:225], 0, s[86:87]
	s_mov_b32 m0, s15
	s_nop 0
	global_load_lds_dwordx4 v[178:179], off
	s_barrier
; #define SHI(lane, v, src) shfl_idx(lane, (v), (src))
; #define PG8_STAGE(bufoff, gbase, voff) do { _Pragma("unroll") for (int _i = 0; _i < 2; ++_i) \
;         __builtin_amdgcn_global_load_lds((const unsigned*)((const char*)(gbase) + (voff)[_i]), (LAS unsigned*)(lds + (bufoff) + ldsw + _i * 8192), 16, 0, 0); } while (0)
; #define PG8_WAIT_V(n) asm volatile("s_waitcnt vmcnt(" #n ")" ::: "memory")
; #define PG8_WAIT_L(n) asm volatile("s_waitcnt lgkmcnt(" #n ")" ::: "memory")
; #define PG8_BAR __builtin_amdgcn_s_barrier()
; #define PG8_SCHED __builtin_amdgcn_sched_barrier(0)
; template <class Epi, class Sched, bool AREMAP>
; __device__ __forceinline__ void gemm_phase(LAS unsigned char* lds, const Gemm g, const Sched& S, const Epi& E, int wv) {
;     ...
;             PG8_BAR; PG8_WAIT_L(0); PG8_MMA(1, 0, At, B0); PG8_BAR; PG8_SCHED;
;             PG8_STAGE(PG8_SB(1, 1), b3 + hstepB, voffB);
;             PG8_WAIT_V(6); PG8_BAR; PG8_MMA(1, 1, At, B1); PG8_BAR;
;     __device__ __forceinline__ void operator()(const f32x4 (&acc)[2][2][4][2], const Unit& u, int wr, int wc, int fr, int fq) const {
;         const int lane = fq * 16 + fr;
;         const int ch0 = u.pn * 128 + wc * 32 + 8 * fq;
;         const int seg = u.pm * 2 + wr, tok0 = seg * 128 + fr;
;         const int src1 = (lane & 48) | ((fr + 15) & 15), src2 = (lane & 48) | ((fr + 14) & 15);
; #pragma unroll
;         for (int n = 0; n < 2; ++n) {
;             const int ch = ch0 + 4 * n;
;             f32x4 wv[3], wg[3];
; #pragma unroll
;             for (int k = 0; k < 3; ++k) { wv[k] = *(const f32x4*)(cw + k * NUP + ch); wg[k] = *(const f32x4*)(cw + k * NUP + DFF + ch); }
;             f32x4 pv1 = {0.f, 0.f, 0.f, 0.f}, pv2 = pv1, pg1 = pv1, pg2 = pv1;
; #pragma unroll
;             for (int q = 0; q < 8; ++q) {
;                 const int ai = q >> 2, m = q & 3;
;                 const f32x4 av = acc[ai][0][m][n], ag = acc[ai][1][m][n];
;                 f32x4 rv1, rv2, rg1, rg2;
; #pragma unroll
;                 for (int j = 0; j < 4; ++j) { rv1[j] = SHI(lane, av[j], src1); rv2[j] = SHI(lane, av[j], src2); rg1[j] = SHI(lane, ag[j], src1); rg2[j] = SHI(lane, ag[j], src2); }
;                 const f32x4 sv1 = fr >= 1 ? rv1 : pv1, sv2 = fr >= 2 ? rv2 : pv2, sg1 = fr >= 1 ? rg1 : pg1, sg2 = fr >= 2 ? rg2 : pg2;
;                 const f32x4 ov = wv[2] * av + wv[1] * sv1 + wv[0] * sv2;
	s_waitcnt lgkmcnt(0)
	s_setprio 1
	s_waitcnt lgkmcnt(0)
	v_mfma_f32_16x16x32_bf16 v[94:97], v[130:133], v[146:149], v[94:97]
	v_mfma_f32_16x16x32_bf16 v[30:33], v[138:141], v[146:149], v[30:33]
	v_mfma_f32_16x16x32_bf16 v[86:89], v[130:133], v[170:173], v[86:89]
	v_mfma_f32_16x16x32_bf16 v[22:25], v[138:141], v[170:173], v[22:25]
	v_mfma_f32_16x16x32_bf16 v[78:81], v[130:133], v[184:187], v[78:81]
	v_mfma_f32_16x16x32_bf16 v[14:17], v[138:141], v[184:187], v[14:17]
	v_mfma_f32_16x16x32_bf16 v[70:73], v[130:133], v[196:199], v[70:73]
	v_mfma_f32_16x16x32_bf16 v[6:9], v[138:141], v[196:199], v[6:9]
	v_mfma_f32_16x16x32_bf16 v[94:97], v[134:137], v[150:153], v[94:97]
	v_mfma_f32_16x16x32_bf16 v[30:33], v[142:145], v[150:153], v[30:33]
	v_mfma_f32_16x16x32_bf16 v[86:89], v[134:137], v[174:177], v[86:89]
	v_mfma_f32_16x16x32_bf16 v[22:25], v[142:145], v[174:177], v[22:25]
	v_mfma_f32_16x16x32_bf16 v[78:81], v[134:137], v[192:195], v[78:81]
	v_mfma_f32_16x16x32_bf16 v[14:17], v[142:145], v[192:195], v[14:17]
	v_mfma_f32_16x16x32_bf16 v[70:73], v[134:137], v[200:203], v[70:73]
	v_mfma_f32_16x16x32_bf16 v[6:9], v[142:145], v[200:203], v[6:9]
	s_setprio 0
	s_barrier
	s_add_u32 s38, s80, 0x80080
	s_addc_u32 s39, s81, 0
	s_add_i32 s33, s58, s91
	v_lshl_add_u64 v[130:131], s[38:39], 0, v[158:159]
	s_mov_b32 m0, s33
	s_nop 0
	global_load_lds_dwordx4 v[130:131], off
	v_lshl_add_u64 v[130:131], s[38:39], 0, v[154:155]
	s_add_i32 m0, s33, 0x2000
	s_nop 0
	global_load_lds_dwordx4 v[130:131], off
	s_waitcnt vmcnt(6)
	s_barrier
	s_setprio 1
	v_mfma_f32_16x16x32_bf16 v[90:93], v[204:207], v[146:149], v[90:93]
	v_mfma_f32_16x16x32_bf16 v[26:29], v[212:215], v[146:149], v[26:29]
	v_mfma_f32_16x16x32_bf16 v[82:85], v[204:207], v[170:173], v[82:85]
	v_mfma_f32_16x16x32_bf16 v[18:21], v[212:215], v[170:173], v[18:21]
	v_mfma_f32_16x16x32_bf16 v[74:77], v[204:207], v[184:187], v[74:77]
	v_mfma_f32_16x16x32_bf16 v[10:13], v[212:215], v[184:187], v[10:13]
	v_mfma_f32_16x16x32_bf16 v[66:69], v[204:207], v[196:199], v[66:69]
	v_mfma_f32_16x16x32_bf16 v[2:5], v[212:215], v[196:199], v[2:5]
	v_mfma_f32_16x16x32_bf16 v[90:93], v[208:211], v[150:153], v[90:93]
	v_mfma_f32_16x16x32_bf16 v[26:29], v[216:219], v[150:153], v[26:29]
	v_mfma_f32_16x16x32_bf16 v[82:85], v[208:211], v[174:177], v[82:85]
	v_mfma_f32_16x16x32_bf16 v[18:21], v[216:219], v[174:177], v[18:21]
	v_mfma_f32_16x16x32_bf16 v[74:77], v[208:211], v[192:195], v[74:77]
	v_mfma_f32_16x16x32_bf16 v[10:13], v[216:219], v[192:195], v[10:13]
	v_mfma_f32_16x16x32_bf16 v[66:69], v[208:211], v[200:203], v[66:69]
	v_mfma_f32_16x16x32_bf16 v[2:5], v[216:219], v[200:203], v[2:5]
	s_setprio 0
	s_add_i32 vcc_hi, vcc_hi, 2
	s_add_u32 s77, s77, 0x100
	s_addc_u32 vcc_lo, vcc_lo, 0
	s_add_u32 s78, s78, 0x100
	s_addc_u32 s79, s79, 0
	s_cmp_gt_u32 vcc_hi, 29
	s_barrier
	s_cbranch_scc0 .LBB0_619
	v_lshl_or_b32 v170, s37, 7, v182
	s_lshl_b32 s37, s76, 1
	s_add_i32 s46, s37, s75
	s_ashr_i32 s47, s46, 31
	s_lshl_b64 s[76:77], s[46:47], 2
	v_lshl_add_u64 v[130:131], s[76:77], 0, v[162:163]
	s_mov_b32 s33, 0xb000
	v_ashrrev_i32_e32 v171, 31, v170
	v_lshl_or_b32 v184, s46, 7, v162
	v_mad_u64_u32 v[176:177], s[46:47], v130, s33, 0
	v_lshlrev_b64 v[142:143], 2, v[170:171]
	v_mad_i32_i24 v177, v131, s33, v177
	v_lshl_add_u64 v[130:131], s[24:25], 0, v[142:143]
	v_lshl_add_u64 v[138:139], s[26:27], 0, v[142:143]
	global_load_dwordx4 v[130:133], v[130:131], off
	v_lshl_add_u64 v[144:145], s[30:31], 0, v[142:143]
	global_load_dwordx4 v[146:149], v[138:139], off
	v_lshl_add_u64 v[172:173], s[18:19], 0, v[142:143]
	v_lshl_add_u64 v[138:139], s[28:29], 0, v[142:143]
	global_load_dwordx4 v[150:153], v[144:145], off
	global_load_dwordx4 v[134:137], v[172:173], off
	v_lshl_add_u64 v[142:143], s[34:35], 0, v[142:143]
	global_load_dwordx4 v[138:141], v[138:139], off
	v_mov_b32_dpp v199, v126 row_ror:1 row_mask:0xf bank_mask:0xf
	global_load_dwordx4 v[142:145], v[142:143], off
	v_mov_b32_dpp v204, v127 row_ror:1 row_mask:0xf bank_mask:0xf
	v_mov_b32_dpp v206, v128 row_ror:1 row_mask:0xf bank_mask:0xf
	v_mov_b32_dpp v208, v129 row_ror:1 row_mask:0xf bank_mask:0xf
	v_mov_b32_dpp v196, v126 row_ror:2 row_mask:0xf bank_mask:0xf
	v_mov_b32_dpp v186, v122 row_ror:1 row_mask:0xf bank_mask:0xf
	v_mov_b32_dpp v201, v127 row_ror:2 row_mask:0xf bank_mask:0xf
	v_mov_b32_dpp v198, v123 row_ror:1 row_mask:0xf bank_mask:0xf
	v_mov_b32_dpp v203, v128 row_ror:2 row_mask:0xf bank_mask:0xf
	v_mov_b32_dpp v200, v124 row_ror:1 row_mask:0xf bank_mask:0xf
	v_mov_b32_dpp v207, v129 row_ror:2 row_mask:0xf bank_mask:0xf
	v_mov_b32_dpp v205, v125 row_ror:1 row_mask:0xf bank_mask:0xf
	v_mov_b32_dpp v185, v122 row_ror:2 row_mask:0xf bank_mask:0xf
	v_mov_b32_dpp v187, v123 row_ror:2 row_mask:0xf bank_mask:0xf
	v_mov_b32_dpp v197, v124 row_ror:2 row_mask:0xf bank_mask:0xf
	v_mov_b32_dpp v202, v125 row_ror:2 row_mask:0xf bank_mask:0xf
	s_waitcnt lgkmcnt(0)
	v_cndmask_b32_e64 v175, v204, 0, s[0:1]
	v_cndmask_b32_e64 v174, v199, 0, s[0:1]
	v_cndmask_b32_e64 v179, v208, 0, s[0:1]
	v_cndmask_b32_e64 v178, v206, 0, s[0:1]
	v_cndmask_b32_e64 v193, 0, v201, s[2:3]
	v_cndmask_b32_e64 v192, 0, v196, s[2:3]
	v_cndmask_b32_e64 v195, 0, v207, s[2:3]
	v_cndmask_b32_e64 v194, 0, v203, s[2:3]
	v_cndmask_b32_e64 v211, v198, 0, s[0:1]
	v_cndmask_b32_e64 v210, v186, 0, s[0:1]
	v_cndmask_b32_e64 v213, v205, 0, s[0:1]
	v_cndmask_b32_e64 v212, v200, 0, s[0:1]
	v_cndmask_b32_e64 v215, 0, v187, s[2:3]
	v_cndmask_b32_e64 v214, 0, v185, s[2:3]
	v_cndmask_b32_e64 v217, 0, v202, s[2:3]
	v_cndmask_b32_e64 v216, 0, v197, s[2:3]
	s_movk_i32 s33, 0x2c00
	v_lshl_add_u64 v[176:177], s[22:23], 0, v[176:177]
	v_lshl_add_u64 v[176:177], v[170:171], 2, v[176:177]
	s_waitcnt vmcnt(0)
; __device__ __forceinline__ unsigned cvt_pk_bf16(float lo, float hi) { f32x2_t f = {lo, hi}; bf16x2_t v = __builtin_convertvector(f, bf16x2_t); return __builtin_bit_cast(unsigned, v); }
; __device__ __forceinline__ float sigmoidf_(float x) { return __builtin_amdgcn_rcpf(1.0f + __expf(-x)); }
; #define SHI(lane, v, src) shfl_idx(lane, (v), (src))
;     __device__ __forceinline__ void operator()(const f32x4 (&acc)[2][2][4][2], const Unit& u, int wr, int wc, int fr, int fq) const {
;     ...
;                 for (int j = 0; j < 4; ++j) { rv1[j] = SHI(lane, av[j], src1); rv2[j] = SHI(lane, av[j], src2); rg1[j] = SHI(lane, ag[j], src1); rg2[j] = SHI(lane, ag[j], src2); }
;                 const f32x4 sv1 = fr >= 1 ? rv1 : pv1, sv2 = fr >= 2 ? rv2 : pv2, sg1 = fr >= 1 ? rg1 : pg1, sg2 = fr >= 2 ? rg2 : pg2;
;                 const f32x4 ov = wv[2] * av + wv[1] * sv1 + wv[0] * sv2;
;                 const f32x4 og = wg[2] * ag + wg[1] * sg1 + wg[0] * sg2;
;                 u32x2 w;
;                 w.x = cvt_pk_bf16(og[0] * sigmoidf_(og[0]) * ov[0], og[1] * sigmoidf_(og[1]) * ov[1]);
;                 w.y = cvt_pk_bf16(og[2] * sigmoidf_(og[2]) * ov[2], og[3] * sigmoidf_(og[3]) * ov[3]);
;                 *(u32x2*)(act + (size_t)(tok0 + q * 16) * DFF + ch) = w;
;                 if (q == 0 && fr < 2) { float* hp = halo + ((size_t)seg * 4 + fr) * NUP + ch; *(f32x4*)hp = av; *(f32x4*)(hp + DFF) = ag; }
;                 if (q == 7 && fr >= 14) { float* hp = halo + ((size_t)seg * 4 + (fr - 12)) * NUP + ch; *(f32x4*)hp = av; *(f32x4*)(hp + DFF) = ag; }
;                 pv1 = rv1; pv2 = rv2; pg1 = rg1; pg2 = rg2;
	v_pk_mul_f32 v[178:179], v[148:149], v[178:179]
	v_pk_mul_f32 v[174:175], v[146:147], v[174:175]
	v_pk_fma_f32 v[178:179], v[128:129], v[152:153], v[178:179]
	v_pk_fma_f32 v[174:175], v[126:127], v[150:151], v[174:175]
	v_pk_fma_f32 v[194:195], v[136:137], v[194:195], v[178:179]
	v_pk_fma_f32 v[174:175], v[134:135], v[192:193], v[174:175]
	v_pk_mul_f32 v[178:179], v[140:141], v[212:213]
	v_pk_mul_f32 v[192:193], v[138:139], v[210:211]
	v_pk_fma_f32 v[178:179], v[124:125], v[144:145], v[178:179]
	v_pk_fma_f32 v[192:193], v[122:123], v[142:143], v[192:193]
	v_pk_fma_f32 v[210:211], v[132:133], v[216:217], v[178:179]
	v_pk_fma_f32 v[178:179], v[130:131], v[214:215], v[192:193]
	s_nop 0
	v_mul_f32_e32 v192, 0xbfb8aa3b, v178
	v_mul_f32_e32 v193, 0xbfb8aa3b, v179
	v_exp_f32_e32 v192, v192
	v_exp_f32_e32 v193, v193
	v_add_f32_e32 v192, 1.0, v192
	v_add_f32_e32 v193, 1.0, v193
	v_rcp_f32_e32 v192, v192
	v_rcp_f32_e32 v193, v193
	s_nop 0
	v_pk_mul_f32 v[178:179], v[178:179], v[192:193]
	s_nop 0
	v_pk_mul_f32 v[174:175], v[174:175], v[178:179]
	s_nop 0
	v_cvt_pk_bf16_f32 v178, v174, v175
	v_mul_f32_e32 v174, 0xbfb8aa3b, v210
	v_mul_f32_e32 v175, 0xbfb8aa3b, v211
	v_exp_f32_e32 v174, v174
	v_exp_f32_e32 v175, v175
	v_add_f32_e32 v174, 1.0, v174
	v_add_f32_e32 v175, 1.0, v175
	v_rcp_f32_e32 v174, v174
	v_rcp_f32_e32 v175, v175
	s_nop 0
	v_pk_mul_f32 v[174:175], v[210:211], v[174:175]
	s_nop 0
	v_pk_mul_f32 v[174:175], v[194:195], v[174:175]
	s_nop 0
	v_cvt_pk_bf16_f32 v179, v174, v175
	v_mov_b64_e32 v[174:175], s[20:21]
	v_mad_i64_i32 v[174:175], s[46:47], v184, s33, v[174:175]
	v_lshl_add_u64 v[174:175], v[170:171], 1, v[174:175]
	global_store_dwordx2 v[174:175], v[178:179], off
	s_and_saveexec_b64 s[78:79], s[4:5]
	s_cbranch_execz .LBB0_622
	global_store_dwordx4 v[176:177], v[126:129], off
	s_nop 1
	v_add_co_u32_e32 v126, vcc, 0x5000, v176
	s_nop 1
	v_addc_co_u32_e32 v127, vcc, 0, v177, vcc
	global_store_dwordx4 v[126:127], v[122:125], off offset:2048
.LBB0_622:
	s_or_b64 exec, exec, s[78:79]
	v_mov_b32_dpp v217, v120 row_ror:1 row_mask:0xf bank_mask:0xf
	v_mov_b32_dpp v221, v121 row_ror:1 row_mask:0xf bank_mask:0xf
	v_mov_b32_dpp v211, v114 row_ror:1 row_mask:0xf bank_mask:0xf
	v_mov_b32_dpp v215, v115 row_ror:1 row_mask:0xf bank_mask:0xf
	v_mov_b32_dpp v209, v118 row_ror:1 row_mask:0xf bank_mask:0xf
	v_mov_b32_dpp v213, v119 row_ror:1 row_mask:0xf bank_mask:0xf
	v_mov_b32_dpp v212, v114 row_ror:2 row_mask:0xf bank_mask:0xf
	v_mov_b32_dpp v216, v115 row_ror:2 row_mask:0xf bank_mask:0xf
	v_mov_b32_dpp v219, v116 row_ror:1 row_mask:0xf bank_mask:0xf
	v_mov_b32_dpp v223, v117 row_ror:1 row_mask:0xf bank_mask:0xf
	v_lshl_add_u64 v[124:125], s[76:77], 0, v[164:165]
	s_mov_b32 s33, 0xb000
	v_mov_b32_dpp v220, v116 row_ror:2 row_mask:0xf bank_mask:0xf
	v_mov_b32_dpp v224, v117 row_ror:2 row_mask:0xf bank_mask:0xf
	s_waitcnt lgkmcnt(0)
	v_cndmask_b32_e64 v127, v221, v208, s[0:1]
	v_cndmask_b32_e64 v126, v217, v206, s[0:1]
	v_mad_u64_u32 v[122:123], s[46:47], v124, s33, 0
	v_cndmask_b32_e64 v193, v215, v198, s[0:1]
	v_cndmask_b32_e64 v192, v211, v186, s[0:1]
	v_pk_mul_f32 v[126:127], v[148:149], v[126:127]
	v_mad_i32_i24 v123, v125, s33, v123
	v_mov_b32_dpp v218, v120 row_ror:2 row_mask:0xf bank_mask:0xf
	v_mov_b32_dpp v222, v121 row_ror:2 row_mask:0xf bank_mask:0xf
	v_cndmask_b32_e64 v125, v213, v204, s[0:1]
	v_cndmask_b32_e64 v124, v209, v199, s[0:1]
	v_pk_fma_f32 v[120:121], v[120:121], v[152:153], v[126:127]
	v_pk_mul_f32 v[126:127], v[138:139], v[192:193]
	v_cndmask_b32_e64 v195, v223, v205, s[0:1]
	v_cndmask_b32_e64 v194, v219, v200, s[0:1]
	v_cndmask_b32_e64 v187, v187, v216, s[2:3]
	v_cndmask_b32_e64 v186, v185, v212, s[2:3]
	v_pk_mul_f32 v[124:125], v[146:147], v[124:125]
	v_pk_fma_f32 v[114:115], v[114:115], v[142:143], v[126:127]
	v_mov_b32_dpp v210, v118 row_ror:2 row_mask:0xf bank_mask:0xf
	v_mov_b32_dpp v214, v119 row_ror:2 row_mask:0xf bank_mask:0xf
	v_pk_fma_f32 v[118:119], v[118:119], v[150:151], v[124:125]
	v_pk_mul_f32 v[124:125], v[140:141], v[194:195]
	v_pk_fma_f32 v[114:115], v[130:131], v[186:187], v[114:115]
	v_cndmask_b32_e64 v199, v202, v224, s[2:3]
	v_cndmask_b32_e64 v198, v197, v220, s[2:3]
	v_pk_fma_f32 v[116:117], v[116:117], v[144:145], v[124:125]
	v_mul_f32_e32 v124, 0xbfb8aa3b, v114
	v_mul_f32_e32 v125, 0xbfb8aa3b, v115
	v_exp_f32_e32 v124, v124
	v_exp_f32_e32 v125, v125
	v_pk_fma_f32 v[116:117], v[132:133], v[198:199], v[116:117]
	s_waitcnt lgkmcnt(0)
	v_cndmask_b32_e64 v129, v201, v214, s[2:3]
	v_mul_f32_e32 v126, 0xbfb8aa3b, v116
	v_mul_f32_e32 v127, 0xbfb8aa3b, v117
	v_exp_f32_e32 v126, v126
	v_exp_f32_e32 v127, v127
	v_add_f32_e32 v124, 1.0, v124
	v_add_f32_e32 v125, 1.0, v125
	v_rcp_f32_e32 v124, v124
	v_rcp_f32_e32 v125, v125
	v_add_f32_e32 v126, 1.0, v126
	v_add_f32_e32 v127, 1.0, v127
	v_rcp_f32_e32 v126, v126
	v_rcp_f32_e32 v127, v127
	v_cndmask_b32_e64 v128, v196, v210, s[2:3]
	v_pk_fma_f32 v[118:119], v[134:135], v[128:129], v[118:119]
	v_pk_mul_f32 v[114:115], v[114:115], v[124:125]
	v_cndmask_b32_e64 v179, v207, v222, s[2:3]
	v_cndmask_b32_e64 v178, v203, v218, s[2:3]
	v_pk_mul_f32 v[114:115], v[118:119], v[114:115]
	v_pk_fma_f32 v[120:121], v[136:137], v[178:179], v[120:121]
	v_cvt_pk_bf16_f32 v124, v114, v115
	v_pk_mul_f32 v[114:115], v[116:117], v[126:127]
	v_mov_b32_dpp v203, v112 row_ror:1 row_mask:0xf bank_mask:0xf
	v_mov_b32_dpp v207, v113 row_ror:1 row_mask:0xf bank_mask:0xf
	v_pk_mul_f32 v[114:115], v[120:121], v[114:115]
	v_mov_b32_dpp v197, v106 row_ror:1 row_mask:0xf bank_mask:0xf
	v_mov_b32_dpp v201, v107 row_ror:1 row_mask:0xf bank_mask:0xf
	v_cvt_pk_bf16_f32 v125, v114, v115
	v_or_b32_e32 v114, 16, v184
	v_mov_b64_e32 v[116:117], s[20:21]
	s_movk_i32 s33, 0x2c00
	v_mov_b32_dpp v185, v110 row_ror:1 row_mask:0xf bank_mask:0xf
	v_mov_b32_dpp v199, v111 row_ror:1 row_mask:0xf bank_mask:0xf
	v_mad_i64_i32 v[114:115], s[46:47], v114, s33, v[116:117]
	v_lshlrev_b64 v[118:119], 1, v[170:171]
	v_mov_b32_dpp v198, v106 row_ror:2 row_mask:0xf bank_mask:0xf
	v_mov_b32_dpp v202, v107 row_ror:2 row_mask:0xf bank_mask:0xf
	v_mov_b32_dpp v205, v108 row_ror:1 row_mask:0xf bank_mask:0xf
	v_mov_b32_dpp v225, v109 row_ror:1 row_mask:0xf bank_mask:0xf
	v_lshl_add_u64 v[114:115], v[114:115], 0, v[118:119]
	global_store_dwordx2 v[114:115], v[124:125], off
	v_mov_b32_dpp v206, v108 row_ror:2 row_mask:0xf bank_mask:0xf
	v_mov_b32_dpp v226, v109 row_ror:2 row_mask:0xf bank_mask:0xf
	s_waitcnt lgkmcnt(0)
; __device__ __forceinline__ unsigned cvt_pk_bf16(float lo, float hi) { f32x2_t f = {lo, hi}; bf16x2_t v = __builtin_convertvector(f, bf16x2_t); return __builtin_bit_cast(unsigned, v); }
; __device__ __forceinline__ float sigmoidf_(float x) { return __builtin_amdgcn_rcpf(1.0f + __expf(-x)); }
; #define SHI(lane, v, src) shfl_idx(lane, (v), (src))
;     __device__ __forceinline__ void operator()(const f32x4 (&acc)[2][2][4][2], const Unit& u, int wr, int wc, int fr, int fq) const {
;     ...
;                 for (int j = 0; j < 4; ++j) { rv1[j] = SHI(lane, av[j], src1); rv2[j] = SHI(lane, av[j], src2); rg1[j] = SHI(lane, ag[j], src1); rg2[j] = SHI(lane, ag[j], src2); }
;                 const f32x4 sv1 = fr >= 1 ? rv1 : pv1, sv2 = fr >= 2 ? rv2 : pv2, sg1 = fr >= 1 ? rg1 : pg1, sg2 = fr >= 2 ? rg2 : pg2;
;                 const f32x4 ov = wv[2] * av + wv[1] * sv1 + wv[0] * sv2;
;                 const f32x4 og = wg[2] * ag + wg[1] * sg1 + wg[0] * sg2;
;                 u32x2 w;
;                 w.x = cvt_pk_bf16(og[0] * sigmoidf_(og[0]) * ov[0], og[1] * sigmoidf_(og[1]) * ov[1]);
;                 w.y = cvt_pk_bf16(og[2] * sigmoidf_(og[2]) * ov[2], og[3] * sigmoidf_(og[3]) * ov[3]);
;                 *(u32x2*)(act + (size_t)(tok0 + q * 16) * DFF + ch) = w;
	v_cndmask_b32_e64 v125, v207, v221, s[0:1]
	v_cndmask_b32_e64 v124, v203, v217, s[0:1]
	v_cndmask_b32_e64 v179, v201, v215, s[0:1]
	v_cndmask_b32_e64 v178, v197, v211, s[0:1]
	v_pk_mul_f32 v[124:125], v[148:149], v[124:125]
	v_mov_b32_dpp v204, v112 row_ror:2 row_mask:0xf bank_mask:0xf
	v_mov_b32_dpp v208, v113 row_ror:2 row_mask:0xf bank_mask:0xf
	v_cndmask_b32_e64 v121, v199, v213, s[0:1]
	v_cndmask_b32_e64 v120, v185, v209, s[0:1]
	v_pk_fma_f32 v[112:113], v[112:113], v[152:153], v[124:125]
	v_pk_mul_f32 v[124:125], v[138:139], v[178:179]
	v_cndmask_b32_e64 v187, v225, v223, s[0:1]
	v_cndmask_b32_e64 v186, v205, v219, s[0:1]
	v_cndmask_b32_e64 v193, v216, v202, s[2:3]
	v_cndmask_b32_e64 v192, v212, v198, s[2:3]
	v_pk_mul_f32 v[120:121], v[146:147], v[120:121]
	v_pk_fma_f32 v[106:107], v[106:107], v[142:143], v[124:125]
	v_mov_b32_dpp v196, v110 row_ror:2 row_mask:0xf bank_mask:0xf
	v_mov_b32_dpp v200, v111 row_ror:2 row_mask:0xf bank_mask:0xf
	v_pk_fma_f32 v[110:111], v[110:111], v[150:151], v[120:121]
	v_pk_mul_f32 v[120:121], v[140:141], v[186:187]
	v_pk_fma_f32 v[106:107], v[130:131], v[192:193], v[106:107]
	v_cndmask_b32_e64 v195, v224, v226, s[2:3]
	v_cndmask_b32_e64 v194, v220, v206, s[2:3]
	v_pk_fma_f32 v[108:109], v[108:109], v[144:145], v[120:121]
	v_mul_f32_e32 v120, 0xbfb8aa3b, v106
	v_mul_f32_e32 v121, 0xbfb8aa3b, v107
	v_exp_f32_e32 v120, v120
	v_exp_f32_e32 v121, v121
	v_pk_fma_f32 v[108:109], v[132:133], v[194:195], v[108:109]
	s_waitcnt lgkmcnt(0)
	v_cndmask_b32_e64 v127, v214, v200, s[2:3]
	v_mul_f32_e32 v124, 0xbfb8aa3b, v108
	v_mul_f32_e32 v125, 0xbfb8aa3b, v109
	v_exp_f32_e32 v124, v124
	v_exp_f32_e32 v125, v125
	v_add_f32_e32 v120, 1.0, v120
	v_add_f32_e32 v121, 1.0, v121
	v_rcp_f32_e32 v120, v120
	v_rcp_f32_e32 v121, v121
	v_add_f32_e32 v124, 1.0, v124
	v_add_f32_e32 v125, 1.0, v125
	v_rcp_f32_e32 v124, v124
	v_rcp_f32_e32 v125, v125
	v_cndmask_b32_e64 v126, v210, v196, s[2:3]
	v_pk_fma_f32 v[110:111], v[134:135], v[126:127], v[110:111]
	v_pk_mul_f32 v[106:107], v[106:107], v[120:121]
	v_cndmask_b32_e64 v129, v222, v208, s[2:3]
	v_cndmask_b32_e64 v128, v218, v204, s[2:3]
	v_pk_mul_f32 v[106:107], v[110:111], v[106:107]
	v_pk_fma_f32 v[112:113], v[136:137], v[128:129], v[112:113]
	v_cvt_pk_bf16_f32 v110, v106, v107
	v_pk_mul_f32 v[106:107], v[108:109], v[124:125]
	v_mov_b32_dpp v211, v104 row_ror:1 row_mask:0xf bank_mask:0xf
	v_mov_b32_dpp v215, v105 row_ror:1 row_mask:0xf bank_mask:0xf
	v_pk_mul_f32 v[106:107], v[112:113], v[106:107]
	v_mov_b32_dpp v192, v98 row_ror:1 row_mask:0xf bank_mask:0xf
	v_mov_b32_dpp v209, v99 row_ror:1 row_mask:0xf bank_mask:0xf
	v_cvt_pk_bf16_f32 v111, v106, v107
	v_or_b32_e32 v106, 32, v184
	v_mov_b32_dpp v186, v102 row_ror:1 row_mask:0xf bank_mask:0xf
	v_mov_b32_dpp v194, v103 row_ror:1 row_mask:0xf bank_mask:0xf
	v_mad_i64_i32 v[106:107], s[46:47], v106, s33, v[116:117]
	v_mov_b32_dpp v193, v98 row_ror:2 row_mask:0xf bank_mask:0xf
	v_mov_b32_dpp v210, v99 row_ror:2 row_mask:0xf bank_mask:0xf
	v_mov_b32_dpp v213, v100 row_ror:1 row_mask:0xf bank_mask:0xf
	v_mov_b32_dpp v217, v101 row_ror:1 row_mask:0xf bank_mask:0xf
	v_lshl_add_u64 v[106:107], v[106:107], 0, v[118:119]
	global_store_dwordx2 v[106:107], v[110:111], off
	v_mov_b32_dpp v214, v100 row_ror:2 row_mask:0xf bank_mask:0xf
	v_mov_b32_dpp v218, v101 row_ror:2 row_mask:0xf bank_mask:0xf
	s_waitcnt lgkmcnt(0)
	v_cndmask_b32_e64 v111, v215, v207, s[0:1]
	v_cndmask_b32_e64 v110, v211, v203, s[0:1]
	v_cndmask_b32_e64 v125, v209, v201, s[0:1]
	v_cndmask_b32_e64 v124, v192, v197, s[0:1]
	v_pk_mul_f32 v[110:111], v[148:149], v[110:111]
	v_mov_b32_dpp v212, v104 row_ror:2 row_mask:0xf bank_mask:0xf
	v_mov_b32_dpp v216, v105 row_ror:2 row_mask:0xf bank_mask:0xf
	v_cndmask_b32_e64 v109, v194, v199, s[0:1]
	v_cndmask_b32_e64 v108, v186, v185, s[0:1]
	v_pk_fma_f32 v[104:105], v[104:105], v[152:153], v[110:111]
	v_pk_mul_f32 v[110:111], v[138:139], v[124:125]
	v_cndmask_b32_e64 v127, v217, v225, s[0:1]
	v_cndmask_b32_e64 v126, v213, v205, s[0:1]
	v_cndmask_b32_e64 v129, v202, v210, s[2:3]
	v_cndmask_b32_e64 v128, v198, v193, s[2:3]
	v_pk_mul_f32 v[108:109], v[146:147], v[108:109]
	v_pk_fma_f32 v[98:99], v[98:99], v[142:143], v[110:111]
	v_mov_b32_dpp v187, v102 row_ror:2 row_mask:0xf bank_mask:0xf
	v_mov_b32_dpp v195, v103 row_ror:2 row_mask:0xf bank_mask:0xf
	v_pk_fma_f32 v[102:103], v[102:103], v[150:151], v[108:109]
	v_pk_mul_f32 v[108:109], v[140:141], v[126:127]
	v_pk_fma_f32 v[98:99], v[130:131], v[128:129], v[98:99]
	v_cndmask_b32_e64 v179, v226, v218, s[2:3]
	v_cndmask_b32_e64 v178, v206, v214, s[2:3]
	v_pk_fma_f32 v[100:101], v[100:101], v[144:145], v[108:109]
	v_mul_f32_e32 v108, 0xbfb8aa3b, v98
	v_mul_f32_e32 v109, 0xbfb8aa3b, v99
	v_exp_f32_e32 v108, v108
	v_exp_f32_e32 v109, v109
	v_pk_fma_f32 v[100:101], v[132:133], v[178:179], v[100:101]
	s_waitcnt lgkmcnt(0)
; __device__ __forceinline__ unsigned cvt_pk_bf16(float lo, float hi) { f32x2_t f = {lo, hi}; bf16x2_t v = __builtin_convertvector(f, bf16x2_t); return __builtin_bit_cast(unsigned, v); }
; __device__ __forceinline__ float sigmoidf_(float x) { return __builtin_amdgcn_rcpf(1.0f + __expf(-x)); }
; #define SHI(lane, v, src) shfl_idx(lane, (v), (src))
;     __device__ __forceinline__ void operator()(const f32x4 (&acc)[2][2][4][2], const Unit& u, int wr, int wc, int fr, int fq) const {
;     ...
;                 for (int j = 0; j < 4; ++j) { rv1[j] = SHI(lane, av[j], src1); rv2[j] = SHI(lane, av[j], src2); rg1[j] = SHI(lane, ag[j], src1); rg2[j] = SHI(lane, ag[j], src2); }
;                 const f32x4 sv1 = fr >= 1 ? rv1 : pv1, sv2 = fr >= 2 ? rv2 : pv2, sg1 = fr >= 1 ? rg1 : pg1, sg2 = fr >= 2 ? rg2 : pg2;
;                 const f32x4 ov = wv[2] * av + wv[1] * sv1 + wv[0] * sv2;
;                 const f32x4 og = wg[2] * ag + wg[1] * sg1 + wg[0] * sg2;
;                 u32x2 w;
;                 w.x = cvt_pk_bf16(og[0] * sigmoidf_(og[0]) * ov[0], og[1] * sigmoidf_(og[1]) * ov[1]);
;                 w.y = cvt_pk_bf16(og[2] * sigmoidf_(og[2]) * ov[2], og[3] * sigmoidf_(og[3]) * ov[3]);
;                 *(u32x2*)(act + (size_t)(tok0 + q * 16) * DFF + ch) = w;
	v_cndmask_b32_e64 v113, v200, v195, s[2:3]
	v_mul_f32_e32 v110, 0xbfb8aa3b, v100
	v_mul_f32_e32 v111, 0xbfb8aa3b, v101
	v_exp_f32_e32 v110, v110
	v_exp_f32_e32 v111, v111
	v_add_f32_e32 v108, 1.0, v108
	v_add_f32_e32 v109, 1.0, v109
	v_rcp_f32_e32 v108, v108
	v_rcp_f32_e32 v109, v109
	v_add_f32_e32 v110, 1.0, v110
	v_add_f32_e32 v111, 1.0, v111
	v_rcp_f32_e32 v110, v110
	v_rcp_f32_e32 v111, v111
	v_cndmask_b32_e64 v112, v196, v187, s[2:3]
	v_pk_fma_f32 v[102:103], v[134:135], v[112:113], v[102:103]
	v_pk_mul_f32 v[98:99], v[98:99], v[108:109]
	v_cndmask_b32_e64 v121, v208, v216, s[2:3]
	v_cndmask_b32_e64 v120, v204, v212, s[2:3]
	v_pk_mul_f32 v[98:99], v[102:103], v[98:99]
	v_pk_fma_f32 v[104:105], v[136:137], v[120:121], v[104:105]
	v_cvt_pk_bf16_f32 v102, v98, v99
	v_pk_mul_f32 v[98:99], v[100:101], v[110:111]
	v_mov_b32_dpp v126, v94 row_ror:1 row_mask:0xf bank_mask:0xf
	v_mov_b32_dpp v178, v95 row_ror:1 row_mask:0xf bank_mask:0xf
	v_mov_b32_dpp v197, v96 row_ror:1 row_mask:0xf bank_mask:0xf
	v_mov_b32_dpp v201, v97 row_ror:1 row_mask:0xf bank_mask:0xf
	v_pk_mul_f32 v[98:99], v[104:105], v[98:99]
	v_mov_b32_dpp v128, v90 row_ror:1 row_mask:0xf bank_mask:0xf
	v_mov_b32_dpp v185, v91 row_ror:1 row_mask:0xf bank_mask:0xf
	v_mov_b32_dpp v199, v92 row_ror:1 row_mask:0xf bank_mask:0xf
	v_mov_b32_dpp v203, v93 row_ror:1 row_mask:0xf bank_mask:0xf
	v_cvt_pk_bf16_f32 v103, v98, v99
	v_or_b32_e32 v98, 48, v184
	v_mad_i64_i32 v[98:99], s[46:47], v98, s33, v[116:117]
	v_mov_b32_dpp v129, v90 row_ror:2 row_mask:0xf bank_mask:0xf
	v_mov_b32_dpp v196, v91 row_ror:2 row_mask:0xf bank_mask:0xf
	v_mov_b32_dpp v200, v92 row_ror:2 row_mask:0xf bank_mask:0xf
	v_mov_b32_dpp v204, v93 row_ror:2 row_mask:0xf bank_mask:0xf
	v_lshl_add_u64 v[98:99], v[98:99], 0, v[118:119]
	global_store_dwordx2 v[98:99], v[102:103], off
	s_waitcnt lgkmcnt(0)
	v_cndmask_b32_e64 v101, v178, v194, s[0:1]
	v_cndmask_b32_e64 v100, v126, v186, s[0:1]
	v_cndmask_b32_e64 v103, v201, v215, s[0:1]
	v_cndmask_b32_e64 v102, v197, v211, s[0:1]
	v_cndmask_b32_e64 v111, v185, v209, s[0:1]
	v_cndmask_b32_e64 v110, v128, v192, s[0:1]
	v_cndmask_b32_e64 v113, v203, v217, s[0:1]
	v_cndmask_b32_e64 v112, v199, v213, s[0:1]
	v_pk_mul_f32 v[102:103], v[148:149], v[102:103]
	v_pk_mul_f32 v[100:101], v[146:147], v[100:101]
	v_mov_b32_dpp v127, v94 row_ror:2 row_mask:0xf bank_mask:0xf
	v_mov_b32_dpp v179, v95 row_ror:2 row_mask:0xf bank_mask:0xf
	v_mov_b32_dpp v198, v96 row_ror:2 row_mask:0xf bank_mask:0xf
	v_mov_b32_dpp v202, v97 row_ror:2 row_mask:0xf bank_mask:0xf
	v_pk_fma_f32 v[94:95], v[94:95], v[150:151], v[100:101]
	v_pk_fma_f32 v[96:97], v[96:97], v[152:153], v[102:103]
	v_pk_mul_f32 v[100:101], v[140:141], v[112:113]
	v_pk_mul_f32 v[102:103], v[138:139], v[110:111]
	v_cndmask_b32_e64 v121, v210, v196, s[2:3]
	v_cndmask_b32_e64 v120, v193, v129, s[2:3]
	v_cndmask_b32_e64 v125, v218, v204, s[2:3]
	v_cndmask_b32_e64 v124, v214, v200, s[2:3]
	v_pk_fma_f32 v[90:91], v[90:91], v[142:143], v[102:103]
	v_pk_fma_f32 v[92:93], v[92:93], v[144:145], v[100:101]
	v_pk_fma_f32 v[90:91], v[130:131], v[120:121], v[90:91]
	v_pk_fma_f32 v[92:93], v[132:133], v[124:125], v[92:93]
	v_mul_f32_e32 v100, 0xbfb8aa3b, v90
	v_mul_f32_e32 v101, 0xbfb8aa3b, v91
	v_mul_f32_e32 v102, 0xbfb8aa3b, v92
	v_mul_f32_e32 v103, 0xbfb8aa3b, v93
	v_exp_f32_e32 v100, v100
	v_exp_f32_e32 v101, v101
	v_exp_f32_e32 v102, v102
	v_exp_f32_e32 v103, v103
	v_add_f32_e32 v100, 1.0, v100
	v_add_f32_e32 v101, 1.0, v101
	v_add_f32_e32 v102, 1.0, v102
	v_add_f32_e32 v103, 1.0, v103
	v_rcp_f32_e32 v100, v100
	v_rcp_f32_e32 v101, v101
	v_rcp_f32_e32 v102, v102
	v_rcp_f32_e32 v103, v103
	s_waitcnt lgkmcnt(0)
	v_cndmask_b32_e64 v105, v195, v179, s[2:3]
	v_cndmask_b32_e64 v104, v187, v127, s[2:3]
	v_cndmask_b32_e64 v109, v216, v202, s[2:3]
	v_cndmask_b32_e64 v108, v212, v198, s[2:3]
	v_pk_fma_f32 v[96:97], v[136:137], v[108:109], v[96:97]
	v_pk_fma_f32 v[94:95], v[134:135], v[104:105], v[94:95]
	v_pk_mul_f32 v[90:91], v[90:91], v[100:101]
	v_pk_mul_f32 v[92:93], v[92:93], v[102:103]
	v_mov_b32_dpp v112, v86 row_ror:1 row_mask:0xf bank_mask:0xf
	v_mov_b32_dpp v124, v87 row_ror:1 row_mask:0xf bank_mask:0xf
	v_mov_b32_dpp v192, v88 row_ror:1 row_mask:0xf bank_mask:0xf
	v_mov_b32_dpp v205, v89 row_ror:1 row_mask:0xf bank_mask:0xf
	v_pk_mul_f32 v[90:91], v[94:95], v[90:91]
	v_pk_mul_f32 v[92:93], v[96:97], v[92:93]
	v_mov_b32_dpp v120, v82 row_ror:1 row_mask:0xf bank_mask:0xf
	v_mov_b32_dpp v186, v83 row_ror:1 row_mask:0xf bank_mask:0xf
	v_mov_b32_dpp v194, v84 row_ror:1 row_mask:0xf bank_mask:0xf
	v_mov_b32_dpp v207, v85 row_ror:1 row_mask:0xf bank_mask:0xf
	v_cvt_pk_bf16_f32 v90, v90, v91
	v_cvt_pk_bf16_f32 v91, v92, v93
	v_or_b32_e32 v92, 64, v184
	v_mad_i64_i32 v[92:93], s[46:47], v92, s33, v[116:117]
	v_mov_b32_dpp v121, v82 row_ror:2 row_mask:0xf bank_mask:0xf
	v_mov_b32_dpp v187, v83 row_ror:2 row_mask:0xf bank_mask:0xf
	v_mov_b32_dpp v195, v84 row_ror:2 row_mask:0xf bank_mask:0xf
	v_mov_b32_dpp v208, v85 row_ror:2 row_mask:0xf bank_mask:0xf
	v_lshl_add_u64 v[92:93], v[92:93], 0, v[118:119]
	global_store_dwordx2 v[92:93], v[90:91], off
	s_waitcnt lgkmcnt(0)
; __device__ __forceinline__ unsigned cvt_pk_bf16(float lo, float hi) { f32x2_t f = {lo, hi}; bf16x2_t v = __builtin_convertvector(f, bf16x2_t); return __builtin_bit_cast(unsigned, v); }
; __device__ __forceinline__ float sigmoidf_(float x) { return __builtin_amdgcn_rcpf(1.0f + __expf(-x)); }
; #define SHI(lane, v, src) shfl_idx(lane, (v), (src))
;     __device__ __forceinline__ void operator()(const f32x4 (&acc)[2][2][4][2], const Unit& u, int wr, int wc, int fr, int fq) const {
;     ...
;                 for (int j = 0; j < 4; ++j) { rv1[j] = SHI(lane, av[j], src1); rv2[j] = SHI(lane, av[j], src2); rg1[j] = SHI(lane, ag[j], src1); rg2[j] = SHI(lane, ag[j], src2); }
;                 const f32x4 sv1 = fr >= 1 ? rv1 : pv1, sv2 = fr >= 2 ? rv2 : pv2, sg1 = fr >= 1 ? rg1 : pg1, sg2 = fr >= 2 ? rg2 : pg2;
;                 const f32x4 ov = wv[2] * av + wv[1] * sv1 + wv[0] * sv2;
;                 const f32x4 og = wg[2] * ag + wg[1] * sg1 + wg[0] * sg2;
;                 u32x2 w;
;                 w.x = cvt_pk_bf16(og[0] * sigmoidf_(og[0]) * ov[0], og[1] * sigmoidf_(og[1]) * ov[1]);
;                 w.y = cvt_pk_bf16(og[2] * sigmoidf_(og[2]) * ov[2], og[3] * sigmoidf_(og[3]) * ov[3]);
;                 *(u32x2*)(act + (size_t)(tok0 + q * 16) * DFF + ch) = w;
	v_cndmask_b32_e64 v91, v124, v178, s[0:1]
	v_cndmask_b32_e64 v90, v112, v126, s[0:1]
	v_cndmask_b32_e64 v95, v205, v201, s[0:1]
	v_cndmask_b32_e64 v94, v192, v197, s[0:1]
	v_cndmask_b32_e64 v103, v186, v185, s[0:1]
	v_cndmask_b32_e64 v102, v120, v128, s[0:1]
	v_cndmask_b32_e64 v105, v207, v203, s[0:1]
	v_cndmask_b32_e64 v104, v194, v199, s[0:1]
	v_pk_mul_f32 v[94:95], v[148:149], v[94:95]
	v_pk_mul_f32 v[90:91], v[146:147], v[90:91]
	v_mov_b32_dpp v113, v86 row_ror:2 row_mask:0xf bank_mask:0xf
	v_mov_b32_dpp v125, v87 row_ror:2 row_mask:0xf bank_mask:0xf
	v_mov_b32_dpp v193, v88 row_ror:2 row_mask:0xf bank_mask:0xf
	v_mov_b32_dpp v206, v89 row_ror:2 row_mask:0xf bank_mask:0xf
	v_pk_fma_f32 v[86:87], v[86:87], v[150:151], v[90:91]
	v_pk_fma_f32 v[88:89], v[88:89], v[152:153], v[94:95]
	v_pk_mul_f32 v[90:91], v[140:141], v[104:105]
	v_pk_mul_f32 v[94:95], v[138:139], v[102:103]
	v_cndmask_b32_e64 v109, v196, v187, s[2:3]
	v_cndmask_b32_e64 v108, v129, v121, s[2:3]
	v_cndmask_b32_e64 v111, v204, v208, s[2:3]
	v_cndmask_b32_e64 v110, v200, v195, s[2:3]
	v_pk_fma_f32 v[82:83], v[82:83], v[142:143], v[94:95]
	v_pk_fma_f32 v[84:85], v[84:85], v[144:145], v[90:91]
	v_pk_fma_f32 v[82:83], v[130:131], v[108:109], v[82:83]
	v_pk_fma_f32 v[84:85], v[132:133], v[110:111], v[84:85]
	v_mul_f32_e32 v90, 0xbfb8aa3b, v82
	v_mul_f32_e32 v91, 0xbfb8aa3b, v83
	v_mul_f32_e32 v94, 0xbfb8aa3b, v84
	v_mul_f32_e32 v95, 0xbfb8aa3b, v85
	v_exp_f32_e32 v90, v90
	v_exp_f32_e32 v91, v91
	v_exp_f32_e32 v94, v94
	v_exp_f32_e32 v95, v95
	v_add_f32_e32 v90, 1.0, v90
	v_add_f32_e32 v91, 1.0, v91
	v_add_f32_e32 v94, 1.0, v94
	v_add_f32_e32 v95, 1.0, v95
	v_rcp_f32_e32 v90, v90
	v_rcp_f32_e32 v91, v91
	v_rcp_f32_e32 v94, v94
	v_rcp_f32_e32 v95, v95
	s_waitcnt lgkmcnt(0)
	v_cndmask_b32_e64 v97, v179, v125, s[2:3]
	v_cndmask_b32_e64 v96, v127, v113, s[2:3]
	v_cndmask_b32_e64 v101, v202, v206, s[2:3]
	v_cndmask_b32_e64 v100, v198, v193, s[2:3]
	v_pk_fma_f32 v[88:89], v[136:137], v[100:101], v[88:89]
	v_pk_fma_f32 v[86:87], v[134:135], v[96:97], v[86:87]
	v_pk_mul_f32 v[82:83], v[82:83], v[90:91]
	v_pk_mul_f32 v[84:85], v[84:85], v[94:95]
	v_mov_b32_dpp v104, v78 row_ror:1 row_mask:0xf bank_mask:0xf
	v_mov_b32_dpp v110, v79 row_ror:1 row_mask:0xf bank_mask:0xf
	v_mov_b32_dpp v128, v80 row_ror:1 row_mask:0xf bank_mask:0xf
	v_mov_b32_dpp v185, v81 row_ror:1 row_mask:0xf bank_mask:0xf
	v_pk_mul_f32 v[82:83], v[86:87], v[82:83]
	v_pk_mul_f32 v[84:85], v[88:89], v[84:85]
	v_mov_b32_dpp v108, v74 row_ror:1 row_mask:0xf bank_mask:0xf
	v_mov_b32_dpp v126, v75 row_ror:1 row_mask:0xf bank_mask:0xf
	v_mov_b32_dpp v178, v76 row_ror:1 row_mask:0xf bank_mask:0xf
	v_mov_b32_dpp v197, v77 row_ror:1 row_mask:0xf bank_mask:0xf
	v_cvt_pk_bf16_f32 v82, v82, v83
	v_cvt_pk_bf16_f32 v83, v84, v85
	v_or_b32_e32 v84, 0x50, v184
	v_mad_i64_i32 v[84:85], s[46:47], v84, s33, v[116:117]
	v_mov_b32_dpp v109, v74 row_ror:2 row_mask:0xf bank_mask:0xf
	v_mov_b32_dpp v127, v75 row_ror:2 row_mask:0xf bank_mask:0xf
	v_mov_b32_dpp v179, v76 row_ror:2 row_mask:0xf bank_mask:0xf
	v_mov_b32_dpp v198, v77 row_ror:2 row_mask:0xf bank_mask:0xf
	v_lshl_add_u64 v[94:95], v[84:85], 0, v[118:119]
	global_store_dwordx2 v[94:95], v[82:83], off
	s_waitcnt lgkmcnt(0)
	v_cndmask_b32_e64 v83, v110, v124, s[0:1]
	v_cndmask_b32_e64 v82, v104, v112, s[0:1]
	v_cndmask_b32_e64 v85, v185, v205, s[0:1]
	v_cndmask_b32_e64 v84, v128, v192, s[0:1]
	v_cndmask_b32_e64 v91, v126, v186, s[0:1]
	v_cndmask_b32_e64 v90, v108, v120, s[0:1]
	v_cndmask_b32_e64 v97, v197, v207, s[0:1]
	v_cndmask_b32_e64 v96, v178, v194, s[0:1]
	v_pk_mul_f32 v[84:85], v[148:149], v[84:85]
	v_pk_mul_f32 v[82:83], v[146:147], v[82:83]
	v_mov_b32_dpp v105, v78 row_ror:2 row_mask:0xf bank_mask:0xf
	v_mov_b32_dpp v111, v79 row_ror:2 row_mask:0xf bank_mask:0xf
	v_mov_b32_dpp v129, v80 row_ror:2 row_mask:0xf bank_mask:0xf
	v_mov_b32_dpp v196, v81 row_ror:2 row_mask:0xf bank_mask:0xf
	v_pk_fma_f32 v[78:79], v[78:79], v[150:151], v[82:83]
	v_pk_fma_f32 v[80:81], v[80:81], v[152:153], v[84:85]
	v_pk_mul_f32 v[82:83], v[140:141], v[96:97]
	v_pk_mul_f32 v[84:85], v[138:139], v[90:91]
	v_cndmask_b32_e64 v101, v187, v127, s[2:3]
	v_cndmask_b32_e64 v100, v121, v109, s[2:3]
	v_cndmask_b32_e64 v103, v208, v198, s[2:3]
	v_cndmask_b32_e64 v102, v195, v179, s[2:3]
	v_pk_fma_f32 v[74:75], v[74:75], v[142:143], v[84:85]
	v_pk_fma_f32 v[76:77], v[76:77], v[144:145], v[82:83]
	v_pk_fma_f32 v[74:75], v[130:131], v[100:101], v[74:75]
	v_pk_fma_f32 v[76:77], v[132:133], v[102:103], v[76:77]
	v_mul_f32_e32 v82, 0xbfb8aa3b, v74
	v_mul_f32_e32 v83, 0xbfb8aa3b, v75
	v_mul_f32_e32 v84, 0xbfb8aa3b, v76
	v_mul_f32_e32 v85, 0xbfb8aa3b, v77
	v_exp_f32_e32 v82, v82
	v_exp_f32_e32 v83, v83
	v_exp_f32_e32 v84, v84
	v_exp_f32_e32 v85, v85
	v_add_f32_e32 v82, 1.0, v82
	v_add_f32_e32 v83, 1.0, v83
	v_add_f32_e32 v84, 1.0, v84
	v_add_f32_e32 v85, 1.0, v85
	v_rcp_f32_e32 v82, v82
	v_rcp_f32_e32 v83, v83
	v_rcp_f32_e32 v84, v84
	v_rcp_f32_e32 v85, v85
	s_waitcnt lgkmcnt(0)
; __device__ __forceinline__ unsigned cvt_pk_bf16(float lo, float hi) { f32x2_t f = {lo, hi}; bf16x2_t v = __builtin_convertvector(f, bf16x2_t); return __builtin_bit_cast(unsigned, v); }
; __device__ __forceinline__ float sigmoidf_(float x) { return __builtin_amdgcn_rcpf(1.0f + __expf(-x)); }
; #define SHI(lane, v, src) shfl_idx(lane, (v), (src))
;     __device__ __forceinline__ void operator()(const f32x4 (&acc)[2][2][4][2], const Unit& u, int wr, int wc, int fr, int fq) const {
;     ...
;                 for (int j = 0; j < 4; ++j) { rv1[j] = SHI(lane, av[j], src1); rv2[j] = SHI(lane, av[j], src2); rg1[j] = SHI(lane, ag[j], src1); rg2[j] = SHI(lane, ag[j], src2); }
;                 const f32x4 sv1 = fr >= 1 ? rv1 : pv1, sv2 = fr >= 2 ? rv2 : pv2, sg1 = fr >= 1 ? rg1 : pg1, sg2 = fr >= 2 ? rg2 : pg2;
;                 const f32x4 ov = wv[2] * av + wv[1] * sv1 + wv[0] * sv2;
;                 const f32x4 og = wg[2] * ag + wg[1] * sg1 + wg[0] * sg2;
;                 u32x2 w;
;                 w.x = cvt_pk_bf16(og[0] * sigmoidf_(og[0]) * ov[0], og[1] * sigmoidf_(og[1]) * ov[1]);
;                 w.y = cvt_pk_bf16(og[2] * sigmoidf_(og[2]) * ov[2], og[3] * sigmoidf_(og[3]) * ov[3]);
;                 *(u32x2*)(act + (size_t)(tok0 + q * 16) * DFF + ch) = w;
;                 if (q == 0 && fr < 2) { float* hp = halo + ((size_t)seg * 4 + fr) * NUP + ch; *(f32x4*)hp = av; *(f32x4*)(hp + DFF) = ag; }
;                 if (q == 7 && fr >= 14) { float* hp = halo + ((size_t)seg * 4 + (fr - 12)) * NUP + ch; *(f32x4*)hp = av; *(f32x4*)(hp + DFF) = ag; }
	v_cndmask_b32_e64 v87, v125, v111, s[2:3]
	v_cndmask_b32_e64 v86, v113, v105, s[2:3]
	v_cndmask_b32_e64 v89, v206, v196, s[2:3]
	v_cndmask_b32_e64 v88, v193, v129, s[2:3]
	v_pk_fma_f32 v[80:81], v[136:137], v[88:89], v[80:81]
	v_pk_fma_f32 v[78:79], v[134:135], v[86:87], v[78:79]
	v_pk_mul_f32 v[74:75], v[74:75], v[82:83]
	v_pk_mul_f32 v[76:77], v[76:77], v[84:85]
	v_pk_mul_f32 v[74:75], v[78:79], v[74:75]
	v_pk_mul_f32 v[76:77], v[80:81], v[76:77]
	v_cvt_pk_bf16_f32 v74, v74, v75
	v_cvt_pk_bf16_f32 v75, v76, v77
	v_or_b32_e32 v76, 0x60, v184
	v_mad_i64_i32 v[76:77], s[46:47], v76, s33, v[116:117]
	v_lshl_add_u64 v[96:97], v[76:77], 0, v[118:119]
	global_store_dwordx2 v[96:97], v[74:75], off
	v_mov_b32_dpp v74, v70 row_ror:1 row_mask:0xf bank_mask:0xf
	v_mov_b32_dpp v75, v71 row_ror:1 row_mask:0xf bank_mask:0xf
	v_mov_b32_dpp v76, v72 row_ror:1 row_mask:0xf bank_mask:0xf
	v_mov_b32_dpp v77, v73 row_ror:1 row_mask:0xf bank_mask:0xf
	v_mov_b32_dpp v78, v70 row_ror:2 row_mask:0xf bank_mask:0xf
	v_mov_b32_dpp v82, v66 row_ror:1 row_mask:0xf bank_mask:0xf
	v_mov_b32_dpp v79, v71 row_ror:2 row_mask:0xf bank_mask:0xf
	v_mov_b32_dpp v83, v67 row_ror:1 row_mask:0xf bank_mask:0xf
	v_mov_b32_dpp v80, v72 row_ror:2 row_mask:0xf bank_mask:0xf
	v_mov_b32_dpp v84, v68 row_ror:1 row_mask:0xf bank_mask:0xf
	v_mov_b32_dpp v81, v73 row_ror:2 row_mask:0xf bank_mask:0xf
	v_mov_b32_dpp v85, v69 row_ror:1 row_mask:0xf bank_mask:0xf
	v_mov_b32_dpp v86, v66 row_ror:2 row_mask:0xf bank_mask:0xf
	v_mov_b32_dpp v87, v67 row_ror:2 row_mask:0xf bank_mask:0xf
	v_mov_b32_dpp v88, v68 row_ror:2 row_mask:0xf bank_mask:0xf
	v_mov_b32_dpp v89, v69 row_ror:2 row_mask:0xf bank_mask:0xf
	s_waitcnt lgkmcnt(0)
	v_cndmask_b32_e64 v75, v75, v110, s[0:1]
	v_cndmask_b32_e64 v74, v74, v104, s[0:1]
	v_cndmask_b32_e64 v77, v77, v185, s[0:1]
	v_cndmask_b32_e64 v76, v76, v128, s[0:1]
	v_pk_mul_f32 v[76:77], v[148:149], v[76:77]
	v_pk_mul_f32 v[74:75], v[146:147], v[74:75]
	v_cndmask_b32_e64 v79, v111, v79, s[2:3]
	v_cndmask_b32_e64 v78, v105, v78, s[2:3]
	v_cndmask_b32_e64 v81, v196, v81, s[2:3]
	v_cndmask_b32_e64 v80, v129, v80, s[2:3]
	v_cndmask_b32_e64 v83, v83, v126, s[0:1]
	v_cndmask_b32_e64 v82, v82, v108, s[0:1]
	v_cndmask_b32_e64 v85, v85, v197, s[0:1]
	v_cndmask_b32_e64 v84, v84, v178, s[0:1]
	v_pk_fma_f32 v[74:75], v[70:71], v[150:151], v[74:75]
	v_pk_fma_f32 v[76:77], v[72:73], v[152:153], v[76:77]
	v_pk_fma_f32 v[74:75], v[134:135], v[78:79], v[74:75]
	v_pk_fma_f32 v[76:77], v[136:137], v[80:81], v[76:77]
	v_pk_mul_f32 v[78:79], v[140:141], v[84:85]
	v_pk_mul_f32 v[80:81], v[138:139], v[82:83]
	v_cndmask_b32_e64 v87, v127, v87, s[2:3]
	v_cndmask_b32_e64 v86, v109, v86, s[2:3]
	v_cndmask_b32_e64 v89, v198, v89, s[2:3]
	v_cndmask_b32_e64 v88, v179, v88, s[2:3]
	v_pk_fma_f32 v[80:81], v[66:67], v[142:143], v[80:81]
	v_pk_fma_f32 v[78:79], v[68:69], v[144:145], v[78:79]
	v_pk_fma_f32 v[80:81], v[130:131], v[86:87], v[80:81]
	v_pk_fma_f32 v[78:79], v[132:133], v[88:89], v[78:79]
	v_mul_f32_e32 v82, 0xbfb8aa3b, v80
	v_mul_f32_e32 v83, 0xbfb8aa3b, v81
	v_mul_f32_e32 v84, 0xbfb8aa3b, v78
	v_mul_f32_e32 v85, 0xbfb8aa3b, v79
	v_exp_f32_e32 v82, v82
	v_exp_f32_e32 v83, v83
	v_exp_f32_e32 v84, v84
	v_exp_f32_e32 v85, v85
	v_add_f32_e32 v82, 1.0, v82
	v_add_f32_e32 v83, 1.0, v83
	v_add_f32_e32 v84, 1.0, v84
	v_add_f32_e32 v85, 1.0, v85
	v_rcp_f32_e32 v82, v82
	v_rcp_f32_e32 v83, v83
	v_rcp_f32_e32 v84, v84
	v_rcp_f32_e32 v85, v85
	v_pk_mul_f32 v[80:81], v[80:81], v[82:83]
	s_nop 0
	v_pk_mul_f32 v[74:75], v[74:75], v[80:81]
	v_pk_mul_f32 v[78:79], v[78:79], v[84:85]
	v_cvt_pk_bf16_f32 v74, v74, v75
	v_pk_mul_f32 v[76:77], v[76:77], v[78:79]
	s_nop 0
	v_cvt_pk_bf16_f32 v75, v76, v77
	v_or_b32_e32 v76, 0x70, v184
	v_mad_i64_i32 v[76:77], s[46:47], v76, s33, v[116:117]
	v_lshl_add_u64 v[100:101], v[76:77], 0, v[118:119]
	global_store_dwordx2 v[100:101], v[74:75], off
	v_lshl_add_u64 v[74:75], s[22:23], 0, v[122:123]
	v_lshl_add_u64 v[90:91], v[170:171], 2, v[74:75]
	s_and_saveexec_b64 s[76:77], s[6:7]
	s_cbranch_execz .LBB0_624
	global_store_dwordx4 v[90:91], v[70:73], off
	s_nop 1
	v_add_co_u32_e32 v70, vcc, 0x5000, v90
	s_nop 1
	v_addc_co_u32_e32 v71, vcc, 0, v91, vcc
	global_store_dwordx4 v[70:71], v[66:69], off offset:2048
; __device__ __forceinline__ unsigned cvt_pk_bf16(float lo, float hi) { f32x2_t f = {lo, hi}; bf16x2_t v = __builtin_convertvector(f, bf16x2_t); return __builtin_bit_cast(unsigned, v); }
; __device__ __forceinline__ float sigmoidf_(float x) { return __builtin_amdgcn_rcpf(1.0f + __expf(-x)); }
; #define SHI(lane, v, src) shfl_idx(lane, (v), (src))
;     __device__ __forceinline__ void operator()(const f32x4 (&acc)[2][2][4][2], const Unit& u, int wr, int wc, int fr, int fq) const {
;     ...
;             const int ch = ch0 + 4 * n;
;             f32x4 wv[3], wg[3];
; #pragma unroll
;             for (int k = 0; k < 3; ++k) { wv[k] = *(const f32x4*)(cw + k * NUP + ch); wg[k] = *(const f32x4*)(cw + k * NUP + DFF + ch); }
;             f32x4 pv1 = {0.f, 0.f, 0.f, 0.f}, pv2 = pv1, pg1 = pv1, pg2 = pv1;
; #pragma unroll
;             for (int q = 0; q < 8; ++q) {
;                 const int ai = q >> 2, m = q & 3;
;                 const f32x4 av = acc[ai][0][m][n], ag = acc[ai][1][m][n];
;                 f32x4 rv1, rv2, rg1, rg2;
; #pragma unroll
;                 for (int j = 0; j < 4; ++j) { rv1[j] = SHI(lane, av[j], src1); rv2[j] = SHI(lane, av[j], src2); rg1[j] = SHI(lane, ag[j], src1); rg2[j] = SHI(lane, ag[j], src2); }
;                 const f32x4 sv1 = fr >= 1 ? rv1 : pv1, sv2 = fr >= 2 ? rv2 : pv2, sg1 = fr >= 1 ? rg1 : pg1, sg2 = fr >= 2 ? rg2 : pg2;
;                 const f32x4 ov = wv[2] * av + wv[1] * sv1 + wv[0] * sv2;
;                 const f32x4 og = wg[2] * ag + wg[1] * sg1 + wg[0] * sg2;
;                 u32x2 w;
;                 w.x = cvt_pk_bf16(og[0] * sigmoidf_(og[0]) * ov[0], og[1] * sigmoidf_(og[1]) * ov[1]);
;                 w.y = cvt_pk_bf16(og[2] * sigmoidf_(og[2]) * ov[2], og[3] * sigmoidf_(og[3]) * ov[3]);
;                 *(u32x2*)(act + (size_t)(tok0 + q * 16) * DFF + ch) = w;
;                 if (q == 0 && fr < 2) { float* hp = halo + ((size_t)seg * 4 + fr) * NUP + ch; *(f32x4*)hp = av; *(f32x4*)(hp + DFF) = ag; }
;                 if (q == 7 && fr >= 14) { float* hp = halo + ((size_t)seg * 4 + (fr - 12)) * NUP + ch; *(f32x4*)hp = av; *(f32x4*)(hp + DFF) = ag; }
;                 pv1 = rv1; pv2 = rv2; pg1 = rg1; pg2 = rg2;
.LBB0_624:
	s_or_b64 exec, exec, s[76:77]
	s_nop 0
	v_or_b32_e32 v66, 4, v170
	v_ashrrev_i32_e32 v67, 31, v66
	v_lshlrev_b64 v[66:67], 2, v[66:67]
	v_lshl_add_u64 v[68:69], s[26:27], 0, v[66:67]
	global_load_dwordx4 v[82:85], v[68:69], off
	v_lshl_add_u64 v[68:69], s[28:29], 0, v[66:67]
	global_load_dwordx4 v[70:73], v[68:69], off
	v_lshl_add_u64 v[68:69], s[30:31], 0, v[66:67]
	global_load_dwordx4 v[86:89], v[68:69], off
	v_lshl_add_u64 v[68:69], s[34:35], 0, v[66:67]
	global_load_dwordx4 v[74:77], v[68:69], off
	v_lshl_add_u64 v[66:67], s[24:25], 0, v[66:67]
	global_load_dwordx4 v[66:69], v[66:67], off
	s_nop 0
	global_load_dwordx4 v[78:81], v[172:173], off offset:16
	v_mov_b32_dpp v103, v58 row_ror:1 row_mask:0xf bank_mask:0xf
	v_mov_b32_dpp v108, v59 row_ror:1 row_mask:0xf bank_mask:0xf
	v_mov_b32_dpp v111, v60 row_ror:1 row_mask:0xf bank_mask:0xf
	v_mov_b32_dpp v119, v61 row_ror:1 row_mask:0xf bank_mask:0xf
	v_mov_b32_dpp v102, v58 row_ror:2 row_mask:0xf bank_mask:0xf
	v_mov_b32_dpp v104, v59 row_ror:2 row_mask:0xf bank_mask:0xf
	v_mov_b32_dpp v109, v60 row_ror:2 row_mask:0xf bank_mask:0xf
	v_mov_b32_dpp v116, v61 row_ror:2 row_mask:0xf bank_mask:0xf
	s_waitcnt lgkmcnt(0)
	v_cndmask_b32_e64 v131, v119, 0, s[0:1]
	v_cndmask_b32_e64 v130, v111, 0, s[0:1]
	v_cndmask_b32_e64 v133, v108, 0, s[0:1]
	v_cndmask_b32_e64 v132, v103, 0, s[0:1]
	v_cndmask_b32_e64 v135, 0, v104, s[2:3]
	v_cndmask_b32_e64 v134, 0, v102, s[2:3]
	v_cndmask_b32_e64 v137, 0, v116, s[2:3]
	v_cndmask_b32_e64 v136, 0, v109, s[2:3]
	v_mov_b32_dpp v110, v62 row_ror:1 row_mask:0xf bank_mask:0xf
	v_mov_b32_dpp v117, v63 row_ror:1 row_mask:0xf bank_mask:0xf
	v_mov_b32_dpp v118, v64 row_ror:1 row_mask:0xf bank_mask:0xf
	v_mov_b32_dpp v121, v65 row_ror:1 row_mask:0xf bank_mask:0xf
	v_mov_b32_dpp v105, v62 row_ror:2 row_mask:0xf bank_mask:0xf
	v_mov_b32_dpp v112, v63 row_ror:2 row_mask:0xf bank_mask:0xf
	v_mov_b32_dpp v113, v64 row_ror:2 row_mask:0xf bank_mask:0xf
	v_mov_b32_dpp v120, v65 row_ror:2 row_mask:0xf bank_mask:0xf
	s_waitcnt lgkmcnt(0)
	v_cndmask_b32_e64 v123, v121, 0, s[0:1]
	v_cndmask_b32_e64 v122, v118, 0, s[0:1]
	v_cndmask_b32_e64 v125, v117, 0, s[0:1]
	v_cndmask_b32_e64 v124, v110, 0, s[0:1]
	v_cndmask_b32_e64 v127, 0, v112, s[2:3]
	v_cndmask_b32_e64 v126, 0, v105, s[2:3]
	v_cndmask_b32_e64 v129, 0, v120, s[2:3]
	v_cndmask_b32_e64 v128, 0, v113, s[2:3]
	s_waitcnt vmcnt(0)
	v_pk_mul_f32 v[124:125], v[82:83], v[124:125]
	v_pk_mul_f32 v[122:123], v[84:85], v[122:123]
	v_pk_mul_f32 v[132:133], v[70:71], v[132:133]
	v_pk_mul_f32 v[130:131], v[72:73], v[130:131]
	v_pk_fma_f32 v[122:123], v[64:65], v[88:89], v[122:123]
	v_pk_fma_f32 v[124:125], v[62:63], v[86:87], v[124:125]
	v_pk_fma_f32 v[130:131], v[60:61], v[76:77], v[130:131]
	v_pk_fma_f32 v[132:133], v[58:59], v[74:75], v[132:133]
	v_pk_fma_f32 v[130:131], v[68:69], v[136:137], v[130:131]
	v_pk_fma_f32 v[132:133], v[66:67], v[134:135], v[132:133]
	v_mul_f32_e32 v136, 0xbfb8aa3b, v130
	v_mul_f32_e32 v134, 0xbfb8aa3b, v132
	v_mul_f32_e32 v135, 0xbfb8aa3b, v133
	v_mul_f32_e32 v137, 0xbfb8aa3b, v131
	v_exp_f32_e32 v134, v134
	v_exp_f32_e32 v135, v135
	v_exp_f32_e32 v136, v136
	v_exp_f32_e32 v137, v137
	v_add_f32_e32 v134, 1.0, v134
	v_add_f32_e32 v135, 1.0, v135
	v_add_f32_e32 v136, 1.0, v136
	v_add_f32_e32 v137, 1.0, v137
	v_rcp_f32_e32 v134, v134
	v_rcp_f32_e32 v135, v135
	v_rcp_f32_e32 v136, v136
	v_rcp_f32_e32 v137, v137
	v_pk_fma_f32 v[122:123], v[80:81], v[128:129], v[122:123]
	v_pk_fma_f32 v[124:125], v[78:79], v[126:127], v[124:125]
	v_pk_mul_f32 v[126:127], v[132:133], v[134:135]
	v_pk_mul_f32 v[128:129], v[130:131], v[136:137]
	v_pk_mul_f32 v[124:125], v[124:125], v[126:127]
	v_pk_mul_f32 v[122:123], v[122:123], v[128:129]
	v_cvt_pk_bf16_f32 v124, v124, v125
	v_cvt_pk_bf16_f32 v125, v122, v123
	global_store_dwordx2 v[174:175], v[124:125], off offset:8
	s_and_saveexec_b64 s[76:77], s[4:5]
	v_readlane_b32 s58, v254, 16
	s_mov_b32 s39, 0xb2a5705f
	s_mov_b32 s38, 0x42ce8ed0
	s_cbranch_execz .LBB0_626
	global_store_dwordx4 v[176:177], v[62:65], off offset:16
	s_nop 1
	v_add_co_u32_e32 v62, vcc, 0x5000, v176
	s_nop 1
	v_addc_co_u32_e32 v63, vcc, 0, v177, vcc
	global_store_dwordx4 v[62:63], v[58:61], off offset:2064
.LBB0_626:
	s_or_b64 exec, exec, s[76:77]
	v_mov_b32_dpp v122, v54 row_ror:1 row_mask:0xf bank_mask:0xf
	v_mov_b32_dpp v126, v55 row_ror:1 row_mask:0xf bank_mask:0xf
	v_mov_b32_dpp v130, v56 row_ror:1 row_mask:0xf bank_mask:0xf
	v_mov_b32_dpp v134, v57 row_ror:1 row_mask:0xf bank_mask:0xf
	v_mov_b32_dpp v124, v50 row_ror:1 row_mask:0xf bank_mask:0xf
	v_mov_b32_dpp v127, v55 row_ror:2 row_mask:0xf bank_mask:0xf
	v_mov_b32_dpp v128, v51 row_ror:1 row_mask:0xf bank_mask:0xf
	v_mov_b32_dpp v131, v56 row_ror:2 row_mask:0xf bank_mask:0xf
	v_mov_b32_dpp v132, v52 row_ror:1 row_mask:0xf bank_mask:0xf
	v_mov_b32_dpp v136, v53 row_ror:1 row_mask:0xf bank_mask:0xf
	v_mov_b32_dpp v123, v54 row_ror:2 row_mask:0xf bank_mask:0xf
	v_mov_b32_dpp v125, v50 row_ror:2 row_mask:0xf bank_mask:0xf
	v_mov_b32_dpp v129, v51 row_ror:2 row_mask:0xf bank_mask:0xf
	v_mov_b32_dpp v133, v52 row_ror:2 row_mask:0xf bank_mask:0xf
	v_mov_b32_dpp v137, v53 row_ror:2 row_mask:0xf bank_mask:0xf
	s_waitcnt lgkmcnt(0)
; __device__ __forceinline__ unsigned cvt_pk_bf16(float lo, float hi) { f32x2_t f = {lo, hi}; bf16x2_t v = __builtin_convertvector(f, bf16x2_t); return __builtin_bit_cast(unsigned, v); }
; __device__ __forceinline__ float sigmoidf_(float x) { return __builtin_amdgcn_rcpf(1.0f + __expf(-x)); }
; #define SHI(lane, v, src) shfl_idx(lane, (v), (src))
;     __device__ __forceinline__ void operator()(const f32x4 (&acc)[2][2][4][2], const Unit& u, int wr, int wc, int fr, int fq) const {
;     ...
;                 for (int j = 0; j < 4; ++j) { rv1[j] = SHI(lane, av[j], src1); rv2[j] = SHI(lane, av[j], src2); rg1[j] = SHI(lane, ag[j], src1); rg2[j] = SHI(lane, ag[j], src2); }
;                 const f32x4 sv1 = fr >= 1 ? rv1 : pv1, sv2 = fr >= 2 ? rv2 : pv2, sg1 = fr >= 1 ? rg1 : pg1, sg2 = fr >= 2 ? rg2 : pg2;
;                 const f32x4 ov = wv[2] * av + wv[1] * sv1 + wv[0] * sv2;
;                 const f32x4 og = wg[2] * ag + wg[1] * sg1 + wg[0] * sg2;
;                 u32x2 w;
;                 w.x = cvt_pk_bf16(og[0] * sigmoidf_(og[0]) * ov[0], og[1] * sigmoidf_(og[1]) * ov[1]);
;                 w.y = cvt_pk_bf16(og[2] * sigmoidf_(og[2]) * ov[2], og[3] * sigmoidf_(og[3]) * ov[3]);
;                 *(u32x2*)(act + (size_t)(tok0 + q * 16) * DFF + ch) = w;
	v_cndmask_b32_e64 v59, v126, v117, s[0:1]
	v_cndmask_b32_e64 v58, v122, v110, s[0:1]
	v_cndmask_b32_e64 v61, v134, v121, s[0:1]
	v_cndmask_b32_e64 v60, v130, v118, s[0:1]
	v_cndmask_b32_e64 v63, v112, v127, s[2:3]
	v_cndmask_b32_e64 v64, v113, v131, s[2:3]
	v_cndmask_b32_e64 v113, v128, v108, s[0:1]
	v_cndmask_b32_e64 v112, v124, v103, s[0:1]
	v_cndmask_b32_e64 v119, v136, v119, s[0:1]
	v_cndmask_b32_e64 v118, v132, v111, s[0:1]
	v_pk_mul_f32 v[60:61], v[84:85], v[60:61]
	v_pk_mul_f32 v[58:59], v[82:83], v[58:59]
	v_mov_b32_dpp v135, v57 row_ror:2 row_mask:0xf bank_mask:0xf
	v_pk_fma_f32 v[54:55], v[54:55], v[86:87], v[58:59]
	v_pk_fma_f32 v[56:57], v[56:57], v[88:89], v[60:61]
	v_pk_mul_f32 v[58:59], v[72:73], v[118:119]
	v_pk_mul_f32 v[60:61], v[70:71], v[112:113]
	v_cndmask_b32_e64 v62, v105, v123, s[2:3]
	v_cndmask_b32_e64 v103, v104, v129, s[2:3]
	v_cndmask_b32_e64 v102, v102, v125, s[2:3]
	v_cndmask_b32_e64 v105, v116, v137, s[2:3]
	v_cndmask_b32_e64 v104, v109, v133, s[2:3]
	v_pk_fma_f32 v[50:51], v[50:51], v[74:75], v[60:61]
	v_pk_fma_f32 v[52:53], v[52:53], v[76:77], v[58:59]
	v_pk_fma_f32 v[50:51], v[66:67], v[102:103], v[50:51]
	v_pk_fma_f32 v[52:53], v[68:69], v[104:105], v[52:53]
	v_mul_f32_e32 v58, 0xbfb8aa3b, v50
	v_mul_f32_e32 v59, 0xbfb8aa3b, v51
	v_mul_f32_e32 v60, 0xbfb8aa3b, v52
	v_mul_f32_e32 v61, 0xbfb8aa3b, v53
	v_exp_f32_e32 v58, v58
	v_exp_f32_e32 v59, v59
	v_exp_f32_e32 v60, v60
	v_exp_f32_e32 v61, v61
	v_add_f32_e32 v58, 1.0, v58
	v_add_f32_e32 v59, 1.0, v59
	v_add_f32_e32 v60, 1.0, v60
	v_add_f32_e32 v61, 1.0, v61
	v_rcp_f32_e32 v58, v58
	v_rcp_f32_e32 v59, v59
	v_rcp_f32_e32 v60, v60
	v_rcp_f32_e32 v61, v61
	s_waitcnt lgkmcnt(0)
	v_cndmask_b32_e64 v65, v120, v135, s[2:3]
	v_pk_fma_f32 v[56:57], v[80:81], v[64:65], v[56:57]
	v_pk_fma_f32 v[54:55], v[78:79], v[62:63], v[54:55]
	v_pk_mul_f32 v[50:51], v[50:51], v[58:59]
	v_pk_mul_f32 v[52:53], v[52:53], v[60:61]
	v_pk_mul_f32 v[50:51], v[54:55], v[50:51]
	v_pk_mul_f32 v[52:53], v[56:57], v[52:53]
	v_cvt_pk_bf16_f32 v50, v50, v51
	v_cvt_pk_bf16_f32 v51, v52, v53
	v_mov_b32_dpp v102, v46 row_ror:1 row_mask:0xf bank_mask:0xf
	v_mov_b32_dpp v108, v47 row_ror:1 row_mask:0xf bank_mask:0xf
	v_mov_b32_dpp v112, v48 row_ror:1 row_mask:0xf bank_mask:0xf
	v_mov_b32_dpp v116, v49 row_ror:1 row_mask:0xf bank_mask:0xf
	global_store_dwordx2 v[114:115], v[50:51], off offset:8
	v_mov_b32_dpp v104, v42 row_ror:1 row_mask:0xf bank_mask:0xf
	v_mov_b32_dpp v110, v43 row_ror:1 row_mask:0xf bank_mask:0xf
	v_mov_b32_dpp v114, v44 row_ror:1 row_mask:0xf bank_mask:0xf
	v_mov_b32_dpp v118, v45 row_ror:1 row_mask:0xf bank_mask:0xf
	v_mov_b32_dpp v105, v42 row_ror:2 row_mask:0xf bank_mask:0xf
	v_mov_b32_dpp v111, v43 row_ror:2 row_mask:0xf bank_mask:0xf
	v_mov_b32_dpp v115, v44 row_ror:2 row_mask:0xf bank_mask:0xf
	v_mov_b32_dpp v119, v45 row_ror:2 row_mask:0xf bank_mask:0xf
	s_waitcnt lgkmcnt(0)
	v_cndmask_b32_e64 v51, v108, v126, s[0:1]
	v_cndmask_b32_e64 v50, v102, v122, s[0:1]
	v_cndmask_b32_e64 v53, v116, v134, s[0:1]
	v_cndmask_b32_e64 v52, v112, v130, s[0:1]
	v_cndmask_b32_e64 v59, v110, v128, s[0:1]
	v_cndmask_b32_e64 v58, v104, v124, s[0:1]
	v_cndmask_b32_e64 v61, v118, v136, s[0:1]
	v_cndmask_b32_e64 v60, v114, v132, s[0:1]
	v_pk_mul_f32 v[52:53], v[84:85], v[52:53]
	v_pk_mul_f32 v[50:51], v[82:83], v[50:51]
	v_mov_b32_dpp v103, v46 row_ror:2 row_mask:0xf bank_mask:0xf
	v_mov_b32_dpp v109, v47 row_ror:2 row_mask:0xf bank_mask:0xf
	v_mov_b32_dpp v113, v48 row_ror:2 row_mask:0xf bank_mask:0xf
	v_mov_b32_dpp v117, v49 row_ror:2 row_mask:0xf bank_mask:0xf
	v_pk_fma_f32 v[46:47], v[46:47], v[86:87], v[50:51]
	v_pk_fma_f32 v[48:49], v[48:49], v[88:89], v[52:53]
	v_pk_mul_f32 v[50:51], v[72:73], v[60:61]
	v_pk_mul_f32 v[52:53], v[70:71], v[58:59]
	v_cndmask_b32_e64 v63, v129, v111, s[2:3]
	v_cndmask_b32_e64 v62, v125, v105, s[2:3]
	v_cndmask_b32_e64 v65, v137, v119, s[2:3]
	v_cndmask_b32_e64 v64, v133, v115, s[2:3]
	v_pk_fma_f32 v[42:43], v[42:43], v[74:75], v[52:53]
	v_pk_fma_f32 v[44:45], v[44:45], v[76:77], v[50:51]
	v_pk_fma_f32 v[42:43], v[66:67], v[62:63], v[42:43]
	v_pk_fma_f32 v[44:45], v[68:69], v[64:65], v[44:45]
	v_mul_f32_e32 v50, 0xbfb8aa3b, v42
	v_mul_f32_e32 v51, 0xbfb8aa3b, v43
	v_mul_f32_e32 v52, 0xbfb8aa3b, v44
	v_mul_f32_e32 v53, 0xbfb8aa3b, v45
	v_exp_f32_e32 v50, v50
	v_exp_f32_e32 v51, v51
	v_exp_f32_e32 v52, v52
	v_exp_f32_e32 v53, v53
	v_add_f32_e32 v50, 1.0, v50
	v_add_f32_e32 v51, 1.0, v51
	v_add_f32_e32 v52, 1.0, v52
	v_add_f32_e32 v53, 1.0, v53
	v_rcp_f32_e32 v50, v50
	v_rcp_f32_e32 v51, v51
	v_rcp_f32_e32 v52, v52
	v_rcp_f32_e32 v53, v53
	s_waitcnt lgkmcnt(0)
	v_cndmask_b32_e64 v55, v127, v109, s[2:3]
	v_cndmask_b32_e64 v54, v123, v103, s[2:3]
	v_cndmask_b32_e64 v57, v135, v117, s[2:3]
	v_cndmask_b32_e64 v56, v131, v113, s[2:3]
	v_pk_fma_f32 v[48:49], v[80:81], v[56:57], v[48:49]
	v_pk_fma_f32 v[46:47], v[78:79], v[54:55], v[46:47]
	v_pk_mul_f32 v[42:43], v[42:43], v[50:51]
	v_pk_mul_f32 v[44:45], v[44:45], v[52:53]
	v_pk_mul_f32 v[42:43], v[46:47], v[42:43]
	v_pk_mul_f32 v[44:45], v[48:49], v[44:45]
	v_cvt_pk_bf16_f32 v42, v42, v43
	v_cvt_pk_bf16_f32 v43, v44, v45
	global_store_dwordx2 v[106:107], v[42:43], off offset:8
	v_mov_b32_dpp v58, v38 row_ror:1 row_mask:0xf bank_mask:0xf
	v_mov_b32_dpp v62, v39 row_ror:1 row_mask:0xf bank_mask:0xf
	v_mov_b32_dpp v106, v40 row_ror:1 row_mask:0xf bank_mask:0xf
	v_mov_b32_dpp v122, v41 row_ror:1 row_mask:0xf bank_mask:0xf
	v_mov_b32_dpp v60, v34 row_ror:1 row_mask:0xf bank_mask:0xf
	v_mov_b32_dpp v64, v35 row_ror:1 row_mask:0xf bank_mask:0xf
	v_mov_b32_dpp v120, v36 row_ror:1 row_mask:0xf bank_mask:0xf
	v_mov_b32_dpp v124, v37 row_ror:1 row_mask:0xf bank_mask:0xf
	v_mov_b32_dpp v61, v34 row_ror:2 row_mask:0xf bank_mask:0xf
	v_mov_b32_dpp v65, v35 row_ror:2 row_mask:0xf bank_mask:0xf
	v_mov_b32_dpp v121, v36 row_ror:2 row_mask:0xf bank_mask:0xf
	v_mov_b32_dpp v125, v37 row_ror:2 row_mask:0xf bank_mask:0xf
	s_waitcnt lgkmcnt(0)
; __device__ __forceinline__ unsigned cvt_pk_bf16(float lo, float hi) { f32x2_t f = {lo, hi}; bf16x2_t v = __builtin_convertvector(f, bf16x2_t); return __builtin_bit_cast(unsigned, v); }
; __device__ __forceinline__ float sigmoidf_(float x) { return __builtin_amdgcn_rcpf(1.0f + __expf(-x)); }
; #define SHI(lane, v, src) shfl_idx(lane, (v), (src))
;     __device__ __forceinline__ void operator()(const f32x4 (&acc)[2][2][4][2], const Unit& u, int wr, int wc, int fr, int fq) const {
;     ...
;                 for (int j = 0; j < 4; ++j) { rv1[j] = SHI(lane, av[j], src1); rv2[j] = SHI(lane, av[j], src2); rg1[j] = SHI(lane, ag[j], src1); rg2[j] = SHI(lane, ag[j], src2); }
;                 const f32x4 sv1 = fr >= 1 ? rv1 : pv1, sv2 = fr >= 2 ? rv2 : pv2, sg1 = fr >= 1 ? rg1 : pg1, sg2 = fr >= 2 ? rg2 : pg2;
;                 const f32x4 ov = wv[2] * av + wv[1] * sv1 + wv[0] * sv2;
;                 const f32x4 og = wg[2] * ag + wg[1] * sg1 + wg[0] * sg2;
;                 u32x2 w;
;                 w.x = cvt_pk_bf16(og[0] * sigmoidf_(og[0]) * ov[0], og[1] * sigmoidf_(og[1]) * ov[1]);
;                 w.y = cvt_pk_bf16(og[2] * sigmoidf_(og[2]) * ov[2], og[3] * sigmoidf_(og[3]) * ov[3]);
;                 *(u32x2*)(act + (size_t)(tok0 + q * 16) * DFF + ch) = w;
	v_cndmask_b32_e64 v43, v62, v108, s[0:1]
	v_cndmask_b32_e64 v42, v58, v102, s[0:1]
	v_cndmask_b32_e64 v45, v122, v116, s[0:1]
	v_cndmask_b32_e64 v44, v106, v112, s[0:1]
	v_cndmask_b32_e64 v51, v64, v110, s[0:1]
	v_cndmask_b32_e64 v50, v60, v104, s[0:1]
	v_cndmask_b32_e64 v53, v124, v118, s[0:1]
	v_cndmask_b32_e64 v52, v120, v114, s[0:1]
	v_pk_mul_f32 v[44:45], v[84:85], v[44:45]
	v_pk_mul_f32 v[42:43], v[82:83], v[42:43]
	v_mov_b32_dpp v59, v38 row_ror:2 row_mask:0xf bank_mask:0xf
	v_mov_b32_dpp v63, v39 row_ror:2 row_mask:0xf bank_mask:0xf
	v_mov_b32_dpp v107, v40 row_ror:2 row_mask:0xf bank_mask:0xf
	v_mov_b32_dpp v123, v41 row_ror:2 row_mask:0xf bank_mask:0xf
	v_pk_fma_f32 v[38:39], v[38:39], v[86:87], v[42:43]
	v_pk_fma_f32 v[40:41], v[40:41], v[88:89], v[44:45]
	v_pk_mul_f32 v[42:43], v[72:73], v[52:53]
	v_pk_mul_f32 v[44:45], v[70:71], v[50:51]
	v_cndmask_b32_e64 v55, v111, v65, s[2:3]
	v_cndmask_b32_e64 v54, v105, v61, s[2:3]
	v_cndmask_b32_e64 v57, v119, v125, s[2:3]
	v_cndmask_b32_e64 v56, v115, v121, s[2:3]
	v_pk_fma_f32 v[34:35], v[34:35], v[74:75], v[44:45]
	v_pk_fma_f32 v[36:37], v[36:37], v[76:77], v[42:43]
	v_pk_fma_f32 v[34:35], v[66:67], v[54:55], v[34:35]
	v_pk_fma_f32 v[36:37], v[68:69], v[56:57], v[36:37]
	v_mul_f32_e32 v42, 0xbfb8aa3b, v34
	v_mul_f32_e32 v43, 0xbfb8aa3b, v35
	v_mul_f32_e32 v44, 0xbfb8aa3b, v36
	v_mul_f32_e32 v45, 0xbfb8aa3b, v37
	v_exp_f32_e32 v42, v42
	v_exp_f32_e32 v43, v43
	v_exp_f32_e32 v44, v44
	v_exp_f32_e32 v45, v45
	v_add_f32_e32 v42, 1.0, v42
	v_add_f32_e32 v43, 1.0, v43
	v_add_f32_e32 v44, 1.0, v44
	v_add_f32_e32 v45, 1.0, v45
	v_rcp_f32_e32 v42, v42
	v_rcp_f32_e32 v43, v43
	v_rcp_f32_e32 v44, v44
	v_rcp_f32_e32 v45, v45
	s_waitcnt lgkmcnt(0)
	v_cndmask_b32_e64 v47, v109, v63, s[2:3]
	v_cndmask_b32_e64 v46, v103, v59, s[2:3]
	v_cndmask_b32_e64 v49, v117, v123, s[2:3]
	v_cndmask_b32_e64 v48, v113, v107, s[2:3]
	v_pk_fma_f32 v[40:41], v[80:81], v[48:49], v[40:41]
	v_pk_fma_f32 v[38:39], v[78:79], v[46:47], v[38:39]
	v_pk_mul_f32 v[34:35], v[34:35], v[42:43]
	v_pk_mul_f32 v[36:37], v[36:37], v[44:45]
	v_pk_mul_f32 v[34:35], v[38:39], v[34:35]
	v_pk_mul_f32 v[36:37], v[40:41], v[36:37]
	v_cvt_pk_bf16_f32 v34, v34, v35
	v_cvt_pk_bf16_f32 v35, v36, v37
	global_store_dwordx2 v[98:99], v[34:35], off offset:8
	v_mov_b32_dpp v50, v30 row_ror:1 row_mask:0xf bank_mask:0xf
	v_mov_b32_dpp v54, v31 row_ror:1 row_mask:0xf bank_mask:0xf
	v_mov_b32_dpp v98, v32 row_ror:1 row_mask:0xf bank_mask:0xf
	v_mov_b32_dpp v104, v33 row_ror:1 row_mask:0xf bank_mask:0xf
	v_mov_b32_dpp v52, v26 row_ror:1 row_mask:0xf bank_mask:0xf
	v_mov_b32_dpp v56, v27 row_ror:1 row_mask:0xf bank_mask:0xf
	v_mov_b32_dpp v102, v28 row_ror:1 row_mask:0xf bank_mask:0xf
	v_mov_b32_dpp v108, v29 row_ror:1 row_mask:0xf bank_mask:0xf
	v_mov_b32_dpp v53, v26 row_ror:2 row_mask:0xf bank_mask:0xf
	v_mov_b32_dpp v57, v27 row_ror:2 row_mask:0xf bank_mask:0xf
	v_mov_b32_dpp v103, v28 row_ror:2 row_mask:0xf bank_mask:0xf
	v_mov_b32_dpp v109, v29 row_ror:2 row_mask:0xf bank_mask:0xf
	s_waitcnt lgkmcnt(0)
	v_cndmask_b32_e64 v35, v54, v62, s[0:1]
	v_cndmask_b32_e64 v34, v50, v58, s[0:1]
	v_cndmask_b32_e64 v37, v104, v122, s[0:1]
	v_cndmask_b32_e64 v36, v98, v106, s[0:1]
	v_cndmask_b32_e64 v43, v56, v64, s[0:1]
	v_cndmask_b32_e64 v42, v52, v60, s[0:1]
	v_cndmask_b32_e64 v45, v108, v124, s[0:1]
	v_cndmask_b32_e64 v44, v102, v120, s[0:1]
	v_pk_mul_f32 v[36:37], v[84:85], v[36:37]
	v_pk_mul_f32 v[34:35], v[82:83], v[34:35]
	v_mov_b32_dpp v51, v30 row_ror:2 row_mask:0xf bank_mask:0xf
	v_mov_b32_dpp v55, v31 row_ror:2 row_mask:0xf bank_mask:0xf
	v_mov_b32_dpp v99, v32 row_ror:2 row_mask:0xf bank_mask:0xf
	v_mov_b32_dpp v105, v33 row_ror:2 row_mask:0xf bank_mask:0xf
	v_pk_fma_f32 v[30:31], v[30:31], v[86:87], v[34:35]
	v_pk_fma_f32 v[32:33], v[32:33], v[88:89], v[36:37]
	v_pk_mul_f32 v[34:35], v[72:73], v[44:45]
	v_pk_mul_f32 v[36:37], v[70:71], v[42:43]
	v_cndmask_b32_e64 v47, v65, v57, s[2:3]
	v_cndmask_b32_e64 v46, v61, v53, s[2:3]
	v_cndmask_b32_e64 v49, v125, v109, s[2:3]
	v_cndmask_b32_e64 v48, v121, v103, s[2:3]
	v_pk_fma_f32 v[26:27], v[26:27], v[74:75], v[36:37]
	v_pk_fma_f32 v[28:29], v[28:29], v[76:77], v[34:35]
	v_pk_fma_f32 v[26:27], v[66:67], v[46:47], v[26:27]
	v_pk_fma_f32 v[28:29], v[68:69], v[48:49], v[28:29]
	v_mul_f32_e32 v34, 0xbfb8aa3b, v26
	v_mul_f32_e32 v35, 0xbfb8aa3b, v27
	v_mul_f32_e32 v36, 0xbfb8aa3b, v28
	v_mul_f32_e32 v37, 0xbfb8aa3b, v29
	v_exp_f32_e32 v34, v34
	v_exp_f32_e32 v35, v35
	v_exp_f32_e32 v36, v36
	v_exp_f32_e32 v37, v37
	v_add_f32_e32 v34, 1.0, v34
	v_add_f32_e32 v35, 1.0, v35
	v_add_f32_e32 v36, 1.0, v36
	v_add_f32_e32 v37, 1.0, v37
	v_rcp_f32_e32 v34, v34
	v_rcp_f32_e32 v35, v35
	v_rcp_f32_e32 v36, v36
	v_rcp_f32_e32 v37, v37
	v_mov_b32_dpp v42, v22 row_ror:1 row_mask:0xf bank_mask:0xf
	v_mov_b32_dpp v46, v23 row_ror:1 row_mask:0xf bank_mask:0xf
	v_mov_b32_dpp v58, v24 row_ror:1 row_mask:0xf bank_mask:0xf
	v_mov_b32_dpp v62, v25 row_ror:1 row_mask:0xf bank_mask:0xf
	s_waitcnt lgkmcnt(0)
	v_cndmask_b32_e64 v39, v63, v55, s[2:3]
	v_cndmask_b32_e64 v38, v59, v51, s[2:3]
	v_cndmask_b32_e64 v41, v123, v105, s[2:3]
	v_cndmask_b32_e64 v40, v107, v99, s[2:3]
	v_mov_b32_dpp v44, v18 row_ror:1 row_mask:0xf bank_mask:0xf
	v_mov_b32_dpp v48, v19 row_ror:1 row_mask:0xf bank_mask:0xf
	v_mov_b32_dpp v60, v20 row_ror:1 row_mask:0xf bank_mask:0xf
	v_mov_b32_dpp v64, v21 row_ror:1 row_mask:0xf bank_mask:0xf
	v_pk_fma_f32 v[32:33], v[80:81], v[40:41], v[32:33]
	v_pk_fma_f32 v[30:31], v[78:79], v[38:39], v[30:31]
	v_pk_mul_f32 v[26:27], v[26:27], v[34:35]
	v_pk_mul_f32 v[28:29], v[28:29], v[36:37]
	v_pk_mul_f32 v[26:27], v[30:31], v[26:27]
	v_pk_mul_f32 v[28:29], v[32:33], v[28:29]
	v_mov_b32_dpp v45, v18 row_ror:2 row_mask:0xf bank_mask:0xf
	v_mov_b32_dpp v49, v19 row_ror:2 row_mask:0xf bank_mask:0xf
	v_mov_b32_dpp v61, v20 row_ror:2 row_mask:0xf bank_mask:0xf
	v_mov_b32_dpp v65, v21 row_ror:2 row_mask:0xf bank_mask:0xf
	v_cvt_pk_bf16_f32 v26, v26, v27
	v_cvt_pk_bf16_f32 v27, v28, v29
	global_store_dwordx2 v[92:93], v[26:27], off offset:8
	v_cndmask_b32_e64 v27, v46, v54, s[0:1]
	v_cndmask_b32_e64 v26, v42, v50, s[0:1]
	v_cndmask_b32_e64 v29, v62, v104, s[0:1]
	v_cndmask_b32_e64 v28, v58, v98, s[0:1]
	s_waitcnt lgkmcnt(0)
; __device__ __forceinline__ unsigned cvt_pk_bf16(float lo, float hi) { f32x2_t f = {lo, hi}; bf16x2_t v = __builtin_convertvector(f, bf16x2_t); return __builtin_bit_cast(unsigned, v); }
; __device__ __forceinline__ float sigmoidf_(float x) { return __builtin_amdgcn_rcpf(1.0f + __expf(-x)); }
; #define SHI(lane, v, src) shfl_idx(lane, (v), (src))
;     __device__ __forceinline__ void operator()(const f32x4 (&acc)[2][2][4][2], const Unit& u, int wr, int wc, int fr, int fq) const {
;     ...
;                 for (int j = 0; j < 4; ++j) { rv1[j] = SHI(lane, av[j], src1); rv2[j] = SHI(lane, av[j], src2); rg1[j] = SHI(lane, ag[j], src1); rg2[j] = SHI(lane, ag[j], src2); }
;                 const f32x4 sv1 = fr >= 1 ? rv1 : pv1, sv2 = fr >= 2 ? rv2 : pv2, sg1 = fr >= 1 ? rg1 : pg1, sg2 = fr >= 2 ? rg2 : pg2;
;                 const f32x4 ov = wv[2] * av + wv[1] * sv1 + wv[0] * sv2;
;                 const f32x4 og = wg[2] * ag + wg[1] * sg1 + wg[0] * sg2;
;                 u32x2 w;
;                 w.x = cvt_pk_bf16(og[0] * sigmoidf_(og[0]) * ov[0], og[1] * sigmoidf_(og[1]) * ov[1]);
;                 w.y = cvt_pk_bf16(og[2] * sigmoidf_(og[2]) * ov[2], og[3] * sigmoidf_(og[3]) * ov[3]);
;                 *(u32x2*)(act + (size_t)(tok0 + q * 16) * DFF + ch) = w;
	v_cndmask_b32_e64 v35, v48, v56, s[0:1]
	v_cndmask_b32_e64 v34, v44, v52, s[0:1]
	v_cndmask_b32_e64 v37, v64, v108, s[0:1]
	v_cndmask_b32_e64 v36, v60, v102, s[0:1]
	v_pk_mul_f32 v[28:29], v[84:85], v[28:29]
	v_pk_mul_f32 v[26:27], v[82:83], v[26:27]
	v_mov_b32_dpp v43, v22 row_ror:2 row_mask:0xf bank_mask:0xf
	v_mov_b32_dpp v47, v23 row_ror:2 row_mask:0xf bank_mask:0xf
	v_mov_b32_dpp v59, v24 row_ror:2 row_mask:0xf bank_mask:0xf
	v_mov_b32_dpp v63, v25 row_ror:2 row_mask:0xf bank_mask:0xf
	v_pk_fma_f32 v[22:23], v[22:23], v[86:87], v[26:27]
	v_pk_fma_f32 v[24:25], v[24:25], v[88:89], v[28:29]
	v_pk_mul_f32 v[26:27], v[72:73], v[36:37]
	v_pk_mul_f32 v[28:29], v[70:71], v[34:35]
	v_cndmask_b32_e64 v39, v57, v49, s[2:3]
	v_cndmask_b32_e64 v38, v53, v45, s[2:3]
	v_cndmask_b32_e64 v41, v109, v65, s[2:3]
	v_cndmask_b32_e64 v40, v103, v61, s[2:3]
	v_pk_fma_f32 v[18:19], v[18:19], v[74:75], v[28:29]
	v_pk_fma_f32 v[20:21], v[20:21], v[76:77], v[26:27]
	v_pk_fma_f32 v[18:19], v[66:67], v[38:39], v[18:19]
	v_pk_fma_f32 v[20:21], v[68:69], v[40:41], v[20:21]
	v_mul_f32_e32 v26, 0xbfb8aa3b, v18
	v_mul_f32_e32 v27, 0xbfb8aa3b, v19
	v_mul_f32_e32 v28, 0xbfb8aa3b, v20
	v_mul_f32_e32 v29, 0xbfb8aa3b, v21
	v_exp_f32_e32 v26, v26
	v_exp_f32_e32 v27, v27
	v_exp_f32_e32 v28, v28
	v_exp_f32_e32 v29, v29
	v_add_f32_e32 v26, 1.0, v26
	v_add_f32_e32 v27, 1.0, v27
	v_add_f32_e32 v28, 1.0, v28
	v_add_f32_e32 v29, 1.0, v29
	v_rcp_f32_e32 v26, v26
	v_rcp_f32_e32 v27, v27
	v_rcp_f32_e32 v28, v28
	v_rcp_f32_e32 v29, v29
	v_mov_b32_dpp v34, v14 row_ror:1 row_mask:0xf bank_mask:0xf
	v_mov_b32_dpp v38, v15 row_ror:1 row_mask:0xf bank_mask:0xf
	v_mov_b32_dpp v50, v16 row_ror:1 row_mask:0xf bank_mask:0xf
	v_mov_b32_dpp v54, v17 row_ror:1 row_mask:0xf bank_mask:0xf
	s_waitcnt lgkmcnt(0)
	v_cndmask_b32_e64 v31, v55, v47, s[2:3]
	v_cndmask_b32_e64 v30, v51, v43, s[2:3]
	v_cndmask_b32_e64 v33, v105, v63, s[2:3]
	v_cndmask_b32_e64 v32, v99, v59, s[2:3]
	v_mov_b32_dpp v36, v10 row_ror:1 row_mask:0xf bank_mask:0xf
	v_mov_b32_dpp v40, v11 row_ror:1 row_mask:0xf bank_mask:0xf
	v_mov_b32_dpp v52, v12 row_ror:1 row_mask:0xf bank_mask:0xf
	v_mov_b32_dpp v56, v13 row_ror:1 row_mask:0xf bank_mask:0xf
	v_pk_fma_f32 v[24:25], v[80:81], v[32:33], v[24:25]
	v_pk_fma_f32 v[22:23], v[78:79], v[30:31], v[22:23]
	v_pk_mul_f32 v[18:19], v[18:19], v[26:27]
	v_pk_mul_f32 v[20:21], v[20:21], v[28:29]
	v_pk_mul_f32 v[18:19], v[22:23], v[18:19]
	v_pk_mul_f32 v[20:21], v[24:25], v[20:21]
	v_mov_b32_dpp v37, v10 row_ror:2 row_mask:0xf bank_mask:0xf
	v_mov_b32_dpp v41, v11 row_ror:2 row_mask:0xf bank_mask:0xf
	v_mov_b32_dpp v53, v12 row_ror:2 row_mask:0xf bank_mask:0xf
	v_mov_b32_dpp v57, v13 row_ror:2 row_mask:0xf bank_mask:0xf
	v_cvt_pk_bf16_f32 v18, v18, v19
	v_cvt_pk_bf16_f32 v19, v20, v21
	global_store_dwordx2 v[94:95], v[18:19], off offset:8
	v_cndmask_b32_e64 v19, v38, v46, s[0:1]
	v_cndmask_b32_e64 v18, v34, v42, s[0:1]
	v_cndmask_b32_e64 v21, v54, v62, s[0:1]
	v_cndmask_b32_e64 v20, v50, v58, s[0:1]
	s_waitcnt lgkmcnt(0)
	v_cndmask_b32_e64 v27, v40, v48, s[0:1]
	v_cndmask_b32_e64 v26, v36, v44, s[0:1]
	v_cndmask_b32_e64 v29, v56, v64, s[0:1]
	v_cndmask_b32_e64 v28, v52, v60, s[0:1]
	v_pk_mul_f32 v[20:21], v[84:85], v[20:21]
	v_pk_mul_f32 v[18:19], v[82:83], v[18:19]
	v_mov_b32_dpp v35, v14 row_ror:2 row_mask:0xf bank_mask:0xf
	v_mov_b32_dpp v39, v15 row_ror:2 row_mask:0xf bank_mask:0xf
	v_mov_b32_dpp v51, v16 row_ror:2 row_mask:0xf bank_mask:0xf
	v_mov_b32_dpp v55, v17 row_ror:2 row_mask:0xf bank_mask:0xf
	v_pk_fma_f32 v[14:15], v[14:15], v[86:87], v[18:19]
	v_pk_fma_f32 v[16:17], v[16:17], v[88:89], v[20:21]
	v_pk_mul_f32 v[18:19], v[72:73], v[28:29]
	v_pk_mul_f32 v[20:21], v[70:71], v[26:27]
	v_cndmask_b32_e64 v31, v49, v41, s[2:3]
	v_cndmask_b32_e64 v30, v45, v37, s[2:3]
	v_cndmask_b32_e64 v33, v65, v57, s[2:3]
	v_cndmask_b32_e64 v32, v61, v53, s[2:3]
	v_pk_fma_f32 v[10:11], v[10:11], v[74:75], v[20:21]
	v_pk_fma_f32 v[12:13], v[12:13], v[76:77], v[18:19]
	v_pk_fma_f32 v[10:11], v[66:67], v[30:31], v[10:11]
	v_pk_fma_f32 v[12:13], v[68:69], v[32:33], v[12:13]
	v_mul_f32_e32 v18, 0xbfb8aa3b, v10
	v_mul_f32_e32 v19, 0xbfb8aa3b, v11
	v_mul_f32_e32 v20, 0xbfb8aa3b, v12
	v_mul_f32_e32 v21, 0xbfb8aa3b, v13
	v_exp_f32_e32 v18, v18
	v_exp_f32_e32 v19, v19
	v_exp_f32_e32 v20, v20
	v_exp_f32_e32 v21, v21
	v_add_f32_e32 v18, 1.0, v18
	v_add_f32_e32 v19, 1.0, v19
	v_add_f32_e32 v20, 1.0, v20
	v_add_f32_e32 v21, 1.0, v21
	v_rcp_f32_e32 v18, v18
	v_rcp_f32_e32 v19, v19
	v_rcp_f32_e32 v20, v20
	v_rcp_f32_e32 v21, v21
	s_waitcnt lgkmcnt(0)
; __device__ __forceinline__ unsigned cvt_pk_bf16(float lo, float hi) { f32x2_t f = {lo, hi}; bf16x2_t v = __builtin_convertvector(f, bf16x2_t); return __builtin_bit_cast(unsigned, v); }
; __device__ __forceinline__ float sigmoidf_(float x) { return __builtin_amdgcn_rcpf(1.0f + __expf(-x)); }
; #define SHI(lane, v, src) shfl_idx(lane, (v), (src))
;     __device__ __forceinline__ void operator()(const f32x4 (&acc)[2][2][4][2], const Unit& u, int wr, int wc, int fr, int fq) const {
;     ...
;                 for (int j = 0; j < 4; ++j) { rv1[j] = SHI(lane, av[j], src1); rv2[j] = SHI(lane, av[j], src2); rg1[j] = SHI(lane, ag[j], src1); rg2[j] = SHI(lane, ag[j], src2); }
;                 const f32x4 sv1 = fr >= 1 ? rv1 : pv1, sv2 = fr >= 2 ? rv2 : pv2, sg1 = fr >= 1 ? rg1 : pg1, sg2 = fr >= 2 ? rg2 : pg2;
;                 const f32x4 ov = wv[2] * av + wv[1] * sv1 + wv[0] * sv2;
;                 const f32x4 og = wg[2] * ag + wg[1] * sg1 + wg[0] * sg2;
;                 u32x2 w;
;                 w.x = cvt_pk_bf16(og[0] * sigmoidf_(og[0]) * ov[0], og[1] * sigmoidf_(og[1]) * ov[1]);
;                 w.y = cvt_pk_bf16(og[2] * sigmoidf_(og[2]) * ov[2], og[3] * sigmoidf_(og[3]) * ov[3]);
;                 *(u32x2*)(act + (size_t)(tok0 + q * 16) * DFF + ch) = w;
;                 if (q == 0 && fr < 2) { float* hp = halo + ((size_t)seg * 4 + fr) * NUP + ch; *(f32x4*)hp = av; *(f32x4*)(hp + DFF) = ag; }
;                 if (q == 7 && fr >= 14) { float* hp = halo + ((size_t)seg * 4 + (fr - 12)) * NUP + ch; *(f32x4*)hp = av; *(f32x4*)(hp + DFF) = ag; }
	v_cndmask_b32_e64 v23, v47, v39, s[2:3]
	v_cndmask_b32_e64 v22, v43, v35, s[2:3]
	v_cndmask_b32_e64 v25, v63, v55, s[2:3]
	v_cndmask_b32_e64 v24, v59, v51, s[2:3]
	v_pk_fma_f32 v[16:17], v[80:81], v[24:25], v[16:17]
	v_pk_fma_f32 v[14:15], v[78:79], v[22:23], v[14:15]
	v_pk_mul_f32 v[10:11], v[10:11], v[18:19]
	v_pk_mul_f32 v[12:13], v[12:13], v[20:21]
	v_pk_mul_f32 v[10:11], v[14:15], v[10:11]
	v_pk_mul_f32 v[12:13], v[16:17], v[12:13]
	v_cvt_pk_bf16_f32 v10, v10, v11
	v_cvt_pk_bf16_f32 v11, v12, v13
	global_store_dwordx2 v[96:97], v[10:11], off offset:8
	v_mov_b32_dpp v10, v6 row_ror:1 row_mask:0xf bank_mask:0xf
	v_mov_b32_dpp v11, v7 row_ror:1 row_mask:0xf bank_mask:0xf
	v_mov_b32_dpp v12, v8 row_ror:1 row_mask:0xf bank_mask:0xf
	v_mov_b32_dpp v13, v9 row_ror:1 row_mask:0xf bank_mask:0xf
	v_mov_b32_dpp v14, v6 row_ror:2 row_mask:0xf bank_mask:0xf
	v_mov_b32_dpp v18, v2 row_ror:1 row_mask:0xf bank_mask:0xf
	v_mov_b32_dpp v15, v7 row_ror:2 row_mask:0xf bank_mask:0xf
	v_mov_b32_dpp v19, v3 row_ror:1 row_mask:0xf bank_mask:0xf
	v_mov_b32_dpp v16, v8 row_ror:2 row_mask:0xf bank_mask:0xf
	v_mov_b32_dpp v20, v4 row_ror:1 row_mask:0xf bank_mask:0xf
	v_mov_b32_dpp v17, v9 row_ror:2 row_mask:0xf bank_mask:0xf
	v_mov_b32_dpp v21, v5 row_ror:1 row_mask:0xf bank_mask:0xf
	v_mov_b32_dpp v22, v2 row_ror:2 row_mask:0xf bank_mask:0xf
	v_mov_b32_dpp v23, v3 row_ror:2 row_mask:0xf bank_mask:0xf
	v_mov_b32_dpp v24, v4 row_ror:2 row_mask:0xf bank_mask:0xf
	v_mov_b32_dpp v25, v5 row_ror:2 row_mask:0xf bank_mask:0xf
	s_waitcnt lgkmcnt(0)
	v_cndmask_b32_e64 v11, v11, v38, s[0:1]
	v_cndmask_b32_e64 v10, v10, v34, s[0:1]
	v_cndmask_b32_e64 v13, v13, v54, s[0:1]
	v_cndmask_b32_e64 v12, v12, v50, s[0:1]
	v_pk_mul_f32 v[12:13], v[84:85], v[12:13]
	v_pk_mul_f32 v[10:11], v[82:83], v[10:11]
	v_cndmask_b32_e64 v15, v39, v15, s[2:3]
	v_cndmask_b32_e64 v14, v35, v14, s[2:3]
	v_cndmask_b32_e64 v17, v55, v17, s[2:3]
	v_cndmask_b32_e64 v16, v51, v16, s[2:3]
	v_cndmask_b32_e64 v19, v19, v40, s[0:1]
	v_cndmask_b32_e64 v18, v18, v36, s[0:1]
	v_cndmask_b32_e64 v21, v21, v56, s[0:1]
	v_cndmask_b32_e64 v20, v20, v52, s[0:1]
	v_pk_fma_f32 v[10:11], v[6:7], v[86:87], v[10:11]
	v_pk_fma_f32 v[12:13], v[8:9], v[88:89], v[12:13]
	v_pk_fma_f32 v[10:11], v[78:79], v[14:15], v[10:11]
	v_pk_fma_f32 v[12:13], v[80:81], v[16:17], v[12:13]
	v_pk_mul_f32 v[14:15], v[72:73], v[20:21]
	v_pk_mul_f32 v[16:17], v[70:71], v[18:19]
	v_cndmask_b32_e64 v23, v41, v23, s[2:3]
	v_cndmask_b32_e64 v22, v37, v22, s[2:3]
	v_cndmask_b32_e64 v25, v57, v25, s[2:3]
	v_cndmask_b32_e64 v24, v53, v24, s[2:3]
	v_pk_fma_f32 v[16:17], v[2:3], v[74:75], v[16:17]
	v_pk_fma_f32 v[14:15], v[4:5], v[76:77], v[14:15]
	v_pk_fma_f32 v[16:17], v[66:67], v[22:23], v[16:17]
	v_pk_fma_f32 v[14:15], v[68:69], v[24:25], v[14:15]
	v_mul_f32_e32 v18, 0xbfb8aa3b, v16
	v_mul_f32_e32 v19, 0xbfb8aa3b, v17
	v_mul_f32_e32 v20, 0xbfb8aa3b, v14
	v_mul_f32_e32 v21, 0xbfb8aa3b, v15
	v_exp_f32_e32 v18, v18
	v_exp_f32_e32 v19, v19
	v_exp_f32_e32 v20, v20
	v_exp_f32_e32 v21, v21
	v_add_f32_e32 v18, 1.0, v18
	v_add_f32_e32 v19, 1.0, v19
	v_add_f32_e32 v20, 1.0, v20
	v_add_f32_e32 v21, 1.0, v21
	v_rcp_f32_e32 v18, v18
	v_rcp_f32_e32 v19, v19
	v_rcp_f32_e32 v20, v20
	v_rcp_f32_e32 v21, v21
	v_pk_mul_f32 v[16:17], v[16:17], v[18:19]
	s_nop 0
	v_pk_mul_f32 v[10:11], v[10:11], v[16:17]
	v_pk_mul_f32 v[14:15], v[14:15], v[20:21]
	v_cvt_pk_bf16_f32 v10, v10, v11
	v_pk_mul_f32 v[12:13], v[12:13], v[14:15]
	s_nop 0
	v_cvt_pk_bf16_f32 v11, v12, v13
	global_store_dwordx2 v[100:101], v[10:11], off offset:8
	s_and_saveexec_b64 s[76:77], s[6:7]
	s_cbranch_execz .LBB0_615
	global_store_dwordx4 v[90:91], v[6:9], off offset:16
	s_nop 1
	v_add_co_u32_e32 v6, vcc, 0x5000, v90
	s_nop 1
	v_addc_co_u32_e32 v7, vcc, 0, v91, vcc
	global_store_dwordx4 v[6:7], v[2:5], off offset:2064
	s_branch .LBB0_615
